# K-loops: snake order inside each 8-MFMA k-group (consecutive MFMAs always share one operand quad); on top of v8
# baseline (speedup 1.0000x reference)
; #define PG8_STAGE(bufoff, gbase, voff) do { _Pragma("unroll") for (int _i = 0; _i < 2; ++_i) \
;         __builtin_amdgcn_global_load_lds((const unsigned*)((const char*)(gbase) + (voff)[_i]), (LAS unsigned*)(lds + (bufoff) + ldsw + _i * 8192), 16, 0, 0); } while (0)
; #define PG8_LDA(dst, b, h) do { _Pragma("unroll") for (int m = 0; m < 4; ++m) _Pragma("unroll") for (int k = 0; k < 2; ++k) dst[m][k] = *(const LAS bf16x8*)(lds + PG8_SA(b, h) + aoff + m * 2048 + k * 1024); } while (0)
; #define PG8_LDB(dst, b, h) do { _Pragma("unroll") for (int n = 0; n < 2; ++n) _Pragma("unroll") for (int k = 0; k < 2; ++k) dst[n][k] = *(const LAS bf16x8*)(lds + PG8_SB(b, h) + boff + n * 2048 + k * 1024); } while (0)
; #define PG8_MMA(ai, bj, At, Bt) do { __builtin_amdgcn_s_setprio(1); _Pragma("unroll") for (int m = 0; m < 4; ++m) _Pragma("unroll") for (int n = 0; n < 2; ++n) _Pragma("unroll") for (int k = 0; k < 2; ++k) \
;         acc[ai][bj][m][n] = __builtin_amdgcn_mfma_f32_16x16x32_bf16(Bt[n][k], At[m][k], acc[ai][bj][m][n], 0, 0, 0); __builtin_amdgcn_s_setprio(0); } while (0)
; #define PG8_WAIT_V(n) asm volatile("s_waitcnt vmcnt(" #n ")" ::: "memory")
; #define PG8_WAIT_L(n) asm volatile("s_waitcnt lgkmcnt(" #n ")" ::: "memory")
; #define PG8_BAR __builtin_amdgcn_s_barrier()
; #define PG8_SCHED __builtin_amdgcn_sched_barrier(0)
; template <class Epi, class Sched>
; __device__ __forceinline__ void gemm_phase(LAS unsigned char* lds, const Gemm g, const Sched& S, const Epi& E) {
;     ...
;             PG8_LDB(B0, 0, 0); PG8_LDB(B1, 0, 1); PG8_SCHED; PG8_LDA(At, 0, 0); PG8_STAGE(PG8_SA(1, 1), a1 + hstepA, voffA);
;             PG8_WAIT_V(8); PG8_WAIT_L(0); PG8_BAR; PG8_MMA(0, 0, At, B0); PG8_MMA(0, 1, At, B1); PG8_BAR; PG8_SCHED;
;             PG8_LDA(At, 0, 1); PG8_STAGE(PG8_SB(0, 0), b2, voffB); PG8_STAGE(PG8_SB(0, 1), b2 + hstepB, voffB); PG8_STAGE(PG8_SA(0, 0), a2, voffA);
.LBB0_137:
	s_add_u32 s28, s26, 0xfff80080
	s_addc_u32 s29, s27, -1
	s_add_i32 s60, 0, 0x10000
	s_cmp_eq_u32 s59, 28
	s_cselect_b32 s41, s21, s29
	s_cselect_b32 s40, s55, s28
	s_cselect_b32 s29, s19, s58
	s_cselect_b32 s28, s56, s57
	s_add_i32 s62, 0, 0x14000
	v_add_u32_e32 v154, s60, v159
	v_add_u32_e32 v174, s62, v159
	ds_read_b128 v[142:145], v154
	ds_read_b128 v[146:149], v154 offset:1024
	ds_read_b128 v[150:153], v154 offset:2048
	ds_read_b128 v[154:157], v154 offset:3072
	ds_read_b128 v[162:165], v174
	ds_read_b128 v[166:169], v174 offset:1024
	ds_read_b128 v[170:173], v174 offset:2048
	ds_read_b128 v[174:177], v174 offset:3072
	v_lshl_add_u64 v[224:225], s[26:27], 0, v[138:139]
	s_add_i32 m0, s46, 0xc000
	ds_read_b128 v[178:181], v161
	ds_read_b128 v[182:185], v161 offset:1024
	ds_read_b128 v[186:189], v161 offset:2048
	ds_read_b128 v[190:193], v161 offset:3072
	ds_read_b128 v[194:197], v161 offset:4096
	ds_read_b128 v[212:215], v161 offset:5120
	ds_read_b128 v[216:219], v161 offset:6144
	ds_read_b128 v[220:223], v161 offset:7168
	global_load_lds_dwordx4 v[224:225], off
	v_lshl_add_u64 v[224:225], s[26:27], 0, v[140:141]
	s_add_i32 m0, s46, 0xe000
	s_nop 0
	global_load_lds_dwordx4 v[224:225], off
	s_waitcnt vmcnt(8)
	s_waitcnt lgkmcnt(0)
	s_barrier
	s_setprio 1
	s_waitcnt lgkmcnt(0)
	v_mfma_f32_16x16x32_bf16 v[130:133], v[142:145], v[178:181], v[130:133]
	v_mfma_f32_16x16x32_bf16 v[122:125], v[150:153], v[178:181], v[122:125]
	v_mfma_f32_16x16x32_bf16 v[106:109], v[150:153], v[186:189], v[106:109]
	v_mfma_f32_16x16x32_bf16 v[114:117], v[142:145], v[186:189], v[114:117]
	v_mfma_f32_16x16x32_bf16 v[98:101], v[142:145], v[194:197], v[98:101]
	v_mfma_f32_16x16x32_bf16 v[90:93], v[150:153], v[194:197], v[90:93]
	v_mfma_f32_16x16x32_bf16 v[74:77], v[150:153], v[216:219], v[74:77]
	v_mfma_f32_16x16x32_bf16 v[82:85], v[142:145], v[216:219], v[82:85]
	v_mfma_f32_16x16x32_bf16 v[130:133], v[146:149], v[182:185], v[130:133]
	v_mfma_f32_16x16x32_bf16 v[122:125], v[154:157], v[182:185], v[122:125]
	v_mfma_f32_16x16x32_bf16 v[106:109], v[154:157], v[190:193], v[106:109]
	v_mfma_f32_16x16x32_bf16 v[114:117], v[146:149], v[190:193], v[114:117]
	v_mfma_f32_16x16x32_bf16 v[98:101], v[146:149], v[212:215], v[98:101]
	v_mfma_f32_16x16x32_bf16 v[90:93], v[154:157], v[212:215], v[90:93]
	v_mfma_f32_16x16x32_bf16 v[74:77], v[154:157], v[220:223], v[74:77]
	v_mfma_f32_16x16x32_bf16 v[82:85], v[146:149], v[220:223], v[82:85]
	s_setprio 0
	s_setprio 1
	v_mfma_f32_16x16x32_bf16 v[126:129], v[162:165], v[178:181], v[126:129]
	v_mfma_f32_16x16x32_bf16 v[118:121], v[170:173], v[178:181], v[118:121]
	v_mfma_f32_16x16x32_bf16 v[102:105], v[170:173], v[186:189], v[102:105]
	v_mfma_f32_16x16x32_bf16 v[110:113], v[162:165], v[186:189], v[110:113]
	v_mfma_f32_16x16x32_bf16 v[94:97], v[162:165], v[194:197], v[94:97]
	v_mfma_f32_16x16x32_bf16 v[86:89], v[170:173], v[194:197], v[86:89]
	v_mfma_f32_16x16x32_bf16 v[70:73], v[170:173], v[216:219], v[70:73]
	v_mfma_f32_16x16x32_bf16 v[78:81], v[162:165], v[216:219], v[78:81]
	v_mfma_f32_16x16x32_bf16 v[126:129], v[166:169], v[182:185], v[126:129]
	v_mfma_f32_16x16x32_bf16 v[118:121], v[174:177], v[182:185], v[118:121]
	v_mfma_f32_16x16x32_bf16 v[102:105], v[174:177], v[190:193], v[102:105]
	v_mfma_f32_16x16x32_bf16 v[110:113], v[166:169], v[190:193], v[110:113]
	v_mfma_f32_16x16x32_bf16 v[94:97], v[166:169], v[212:215], v[94:97]
	v_mfma_f32_16x16x32_bf16 v[86:89], v[174:177], v[212:215], v[86:89]
	v_mfma_f32_16x16x32_bf16 v[70:73], v[174:177], v[220:223], v[70:73]
	v_mfma_f32_16x16x32_bf16 v[78:81], v[166:169], v[220:223], v[78:81]
	s_setprio 0
	s_barrier
	s_add_i32 s60, s60, s45
	v_lshl_add_u64 v[224:225], s[28:29], 0, v[4:5]
	s_mov_b32 m0, s60
	ds_read_b128 v[178:181], v161 offset:16384
	ds_read_b128 v[182:185], v161 offset:17408
	ds_read_b128 v[186:189], v161 offset:18432
	ds_read_b128 v[190:193], v161 offset:19456
	ds_read_b128 v[194:197], v161 offset:20480
	ds_read_b128 v[212:215], v161 offset:21504
	ds_read_b128 v[216:219], v161 offset:22528
	ds_read_b128 v[220:223], v161 offset:23552
	global_load_lds_dwordx4 v[224:225], off
	s_add_i32 m0, s60, 0x2000
	s_add_u32 s60, s28, 0x80000
	v_lshl_add_u64 v[226:227], s[28:29], 0, v[2:3]
	s_addc_u32 s61, s29, 0
	s_add_i32 s62, s62, s45
	global_load_lds_dwordx4 v[226:227], off
	v_lshl_add_u64 v[228:229], s[60:61], 0, v[4:5]
	s_mov_b32 m0, s62
	v_lshl_add_u64 v[230:231], s[40:41], 0, v[134:135]
	global_load_lds_dwordx4 v[228:229], off
	v_lshl_add_u64 v[228:229], s[60:61], 0, v[2:3]
	s_add_i32 m0, s62, 0x2000
	s_nop 0
	global_load_lds_dwordx4 v[228:229], off
	v_lshl_add_u64 v[228:229], s[40:41], 0, v[136:137]
	s_mov_b32 m0, s46
	s_nop 0
	global_load_lds_dwordx4 v[228:229], off
	s_mov_b32 m0, s47
	s_nop 0
	global_load_lds_dwordx4 v[230:231], off
	s_waitcnt vmcnt(8)
	s_waitcnt lgkmcnt(0)
	s_barrier
; #define PG8_STAGE(bufoff, gbase, voff) do { _Pragma("unroll") for (int _i = 0; _i < 2; ++_i) \
;         __builtin_amdgcn_global_load_lds((const unsigned*)((const char*)(gbase) + (voff)[_i]), (LAS unsigned*)(lds + (bufoff) + ldsw + _i * 8192), 16, 0, 0); } while (0)
; #define PG8_LDA(dst, b, h) do { _Pragma("unroll") for (int m = 0; m < 4; ++m) _Pragma("unroll") for (int k = 0; k < 2; ++k) dst[m][k] = *(const LAS bf16x8*)(lds + PG8_SA(b, h) + aoff + m * 2048 + k * 1024); } while (0)
; #define PG8_LDB(dst, b, h) do { _Pragma("unroll") for (int n = 0; n < 2; ++n) _Pragma("unroll") for (int k = 0; k < 2; ++k) dst[n][k] = *(const LAS bf16x8*)(lds + PG8_SB(b, h) + boff + n * 2048 + k * 1024); } while (0)
; #define PG8_MMA(ai, bj, At, Bt) do { __builtin_amdgcn_s_setprio(1); _Pragma("unroll") for (int m = 0; m < 4; ++m) _Pragma("unroll") for (int n = 0; n < 2; ++n) _Pragma("unroll") for (int k = 0; k < 2; ++k) \
;         acc[ai][bj][m][n] = __builtin_amdgcn_mfma_f32_16x16x32_bf16(Bt[n][k], At[m][k], acc[ai][bj][m][n], 0, 0, 0); __builtin_amdgcn_s_setprio(0); } while (0)
; #define PG8_WAIT_V(n) asm volatile("s_waitcnt vmcnt(" #n ")" ::: "memory")
; #define PG8_WAIT_L(n) asm volatile("s_waitcnt lgkmcnt(" #n ")" ::: "memory")
; #define PG8_BAR __builtin_amdgcn_s_barrier()
; #define PG8_SCHED __builtin_amdgcn_sched_barrier(0)
; template <class Epi, class Sched>
; __device__ __forceinline__ void gemm_phase(LAS unsigned char* lds, const Gemm g, const Sched& S, const Epi& E) {
;     ...
;             PG8_WAIT_V(8); PG8_WAIT_L(0); PG8_BAR; PG8_MMA(1, 0, At, B0); PG8_MMA(1, 1, At, B1); PG8_BAR; PG8_SCHED;
;             PG8_LDB(B0, 1, 0); PG8_LDB(B1, 1, 1); PG8_SCHED; PG8_LDA(At, 1, 0); PG8_STAGE(PG8_SA(0, 1), a2 + hstepA, voffA);
;             PG8_WAIT_V(8); PG8_WAIT_L(0); PG8_BAR; PG8_MMA(0, 0, At, B0); PG8_MMA(0, 1, At, B1); PG8_BAR; PG8_SCHED;
	s_setprio 1
	s_waitcnt lgkmcnt(0)
	v_mfma_f32_16x16x32_bf16 v[66:69], v[142:145], v[178:181], v[66:69]
	v_mfma_f32_16x16x32_bf16 v[58:61], v[150:153], v[178:181], v[58:61]
	v_mfma_f32_16x16x32_bf16 v[42:45], v[150:153], v[186:189], v[42:45]
	v_mfma_f32_16x16x32_bf16 v[50:53], v[142:145], v[186:189], v[50:53]
	v_mfma_f32_16x16x32_bf16 v[34:37], v[142:145], v[194:197], v[34:37]
	v_mfma_f32_16x16x32_bf16 v[26:29], v[150:153], v[194:197], v[26:29]
	v_mfma_f32_16x16x32_bf16 v[10:13], v[150:153], v[216:219], v[10:13]
	v_mfma_f32_16x16x32_bf16 v[18:21], v[142:145], v[216:219], v[18:21]
	v_mfma_f32_16x16x32_bf16 v[66:69], v[146:149], v[182:185], v[66:69]
	v_mfma_f32_16x16x32_bf16 v[58:61], v[154:157], v[182:185], v[58:61]
	v_mfma_f32_16x16x32_bf16 v[42:45], v[154:157], v[190:193], v[42:45]
	v_mfma_f32_16x16x32_bf16 v[50:53], v[146:149], v[190:193], v[50:53]
	v_mfma_f32_16x16x32_bf16 v[34:37], v[146:149], v[212:215], v[34:37]
	v_mfma_f32_16x16x32_bf16 v[26:29], v[154:157], v[212:215], v[26:29]
	v_mfma_f32_16x16x32_bf16 v[10:13], v[154:157], v[220:223], v[10:13]
	v_mfma_f32_16x16x32_bf16 v[18:21], v[146:149], v[220:223], v[18:21]
	s_setprio 0
	s_setprio 1
	v_mfma_f32_16x16x32_bf16 v[62:65], v[162:165], v[178:181], v[62:65]
	v_mfma_f32_16x16x32_bf16 v[54:57], v[170:173], v[178:181], v[54:57]
	v_mfma_f32_16x16x32_bf16 v[38:41], v[170:173], v[186:189], v[38:41]
	v_mfma_f32_16x16x32_bf16 v[46:49], v[162:165], v[186:189], v[46:49]
	v_mfma_f32_16x16x32_bf16 v[30:33], v[162:165], v[194:197], v[30:33]
	v_mfma_f32_16x16x32_bf16 v[22:25], v[170:173], v[194:197], v[22:25]
	v_mfma_f32_16x16x32_bf16 v[6:9], v[170:173], v[216:219], v[6:9]
	v_mfma_f32_16x16x32_bf16 v[14:17], v[162:165], v[216:219], v[14:17]
	v_mfma_f32_16x16x32_bf16 v[62:65], v[166:169], v[182:185], v[62:65]
	v_mfma_f32_16x16x32_bf16 v[54:57], v[174:177], v[182:185], v[54:57]
	v_mfma_f32_16x16x32_bf16 v[38:41], v[174:177], v[190:193], v[38:41]
	v_mfma_f32_16x16x32_bf16 v[46:49], v[166:169], v[190:193], v[46:49]
	v_mfma_f32_16x16x32_bf16 v[30:33], v[166:169], v[212:215], v[30:33]
	v_mfma_f32_16x16x32_bf16 v[22:25], v[174:177], v[212:215], v[22:25]
	v_mfma_f32_16x16x32_bf16 v[6:9], v[174:177], v[220:223], v[6:9]
	v_mfma_f32_16x16x32_bf16 v[14:17], v[166:169], v[220:223], v[14:17]
	s_setprio 0
	s_barrier
	s_add_i32 s60, 0, 0x18000
	s_add_i32 s61, 0, 0x1c000
	v_add_u32_e32 v154, s60, v159
	v_add_u32_e32 v174, s61, v159
	ds_read_b128 v[142:145], v154
	ds_read_b128 v[146:149], v154 offset:1024
	ds_read_b128 v[150:153], v154 offset:2048
	ds_read_b128 v[154:157], v154 offset:3072
	ds_read_b128 v[162:165], v174
	ds_read_b128 v[166:169], v174 offset:1024
	ds_read_b128 v[170:173], v174 offset:2048
	ds_read_b128 v[174:177], v174 offset:3072
	s_add_u32 s40, s40, 0x80000
	s_addc_u32 s41, s41, 0
	s_mov_b32 m0, s48
	v_lshl_add_u64 v[236:237], s[40:41], 0, v[136:137]
	ds_read_b128 v[178:181], v161 offset:32768
	ds_read_b128 v[182:185], v161 offset:33792
	ds_read_b128 v[186:189], v161 offset:34816
	ds_read_b128 v[190:193], v161 offset:35840
	ds_read_b128 v[194:197], v161 offset:36864
	ds_read_b128 v[212:215], v161 offset:37888
	ds_read_b128 v[216:219], v161 offset:38912
	ds_read_b128 v[220:223], v161 offset:39936
	global_load_lds_dwordx4 v[236:237], off
	v_lshl_add_u64 v[236:237], s[40:41], 0, v[134:135]
	s_mov_b32 m0, s49
	s_nop 0
	global_load_lds_dwordx4 v[236:237], off
	s_waitcnt vmcnt(8)
	s_waitcnt lgkmcnt(0)
	s_barrier
	s_setprio 1
	s_waitcnt lgkmcnt(0)
	v_mfma_f32_16x16x32_bf16 v[130:133], v[142:145], v[178:181], v[130:133]
	v_mfma_f32_16x16x32_bf16 v[122:125], v[150:153], v[178:181], v[122:125]
	v_mfma_f32_16x16x32_bf16 v[106:109], v[150:153], v[186:189], v[106:109]
	v_mfma_f32_16x16x32_bf16 v[114:117], v[142:145], v[186:189], v[114:117]
	v_mfma_f32_16x16x32_bf16 v[98:101], v[142:145], v[194:197], v[98:101]
	v_mfma_f32_16x16x32_bf16 v[90:93], v[150:153], v[194:197], v[90:93]
	v_mfma_f32_16x16x32_bf16 v[74:77], v[150:153], v[216:219], v[74:77]
	v_mfma_f32_16x16x32_bf16 v[82:85], v[142:145], v[216:219], v[82:85]
	v_mfma_f32_16x16x32_bf16 v[130:133], v[146:149], v[182:185], v[130:133]
	v_mfma_f32_16x16x32_bf16 v[122:125], v[154:157], v[182:185], v[122:125]
	v_mfma_f32_16x16x32_bf16 v[106:109], v[154:157], v[190:193], v[106:109]
	v_mfma_f32_16x16x32_bf16 v[114:117], v[146:149], v[190:193], v[114:117]
	v_mfma_f32_16x16x32_bf16 v[98:101], v[146:149], v[212:215], v[98:101]
	v_mfma_f32_16x16x32_bf16 v[90:93], v[154:157], v[212:215], v[90:93]
	v_mfma_f32_16x16x32_bf16 v[74:77], v[154:157], v[220:223], v[74:77]
	v_mfma_f32_16x16x32_bf16 v[82:85], v[146:149], v[220:223], v[82:85]
	s_setprio 0
	s_setprio 1
	v_mfma_f32_16x16x32_bf16 v[126:129], v[162:165], v[178:181], v[126:129]
	v_mfma_f32_16x16x32_bf16 v[118:121], v[170:173], v[178:181], v[118:121]
	v_mfma_f32_16x16x32_bf16 v[102:105], v[170:173], v[186:189], v[102:105]
	v_mfma_f32_16x16x32_bf16 v[110:113], v[162:165], v[186:189], v[110:113]
	v_mfma_f32_16x16x32_bf16 v[94:97], v[162:165], v[194:197], v[94:97]
	v_mfma_f32_16x16x32_bf16 v[86:89], v[170:173], v[194:197], v[86:89]
	v_mfma_f32_16x16x32_bf16 v[70:73], v[170:173], v[216:219], v[70:73]
	v_mfma_f32_16x16x32_bf16 v[78:81], v[162:165], v[216:219], v[78:81]
	v_mfma_f32_16x16x32_bf16 v[126:129], v[166:169], v[182:185], v[126:129]
	v_mfma_f32_16x16x32_bf16 v[118:121], v[174:177], v[182:185], v[118:121]
	v_mfma_f32_16x16x32_bf16 v[102:105], v[174:177], v[190:193], v[102:105]
	v_mfma_f32_16x16x32_bf16 v[110:113], v[166:169], v[190:193], v[110:113]
	v_mfma_f32_16x16x32_bf16 v[94:97], v[166:169], v[212:215], v[94:97]
	v_mfma_f32_16x16x32_bf16 v[86:89], v[174:177], v[212:215], v[86:89]
	v_mfma_f32_16x16x32_bf16 v[70:73], v[174:177], v[220:223], v[70:73]
	v_mfma_f32_16x16x32_bf16 v[78:81], v[166:169], v[220:223], v[78:81]
	s_setprio 0
	s_barrier
; #define PG8_STAGE(bufoff, gbase, voff) do { _Pragma("unroll") for (int _i = 0; _i < 2; ++_i) \
;         __builtin_amdgcn_global_load_lds((const unsigned*)((const char*)(gbase) + (voff)[_i]), (LAS unsigned*)(lds + (bufoff) + ldsw + _i * 8192), 16, 0, 0); } while (0)
; #define PG8_LDA(dst, b, h) do { _Pragma("unroll") for (int m = 0; m < 4; ++m) _Pragma("unroll") for (int k = 0; k < 2; ++k) dst[m][k] = *(const LAS bf16x8*)(lds + PG8_SA(b, h) + aoff + m * 2048 + k * 1024); } while (0)
; #define PG8_MMA(ai, bj, At, Bt) do { __builtin_amdgcn_s_setprio(1); _Pragma("unroll") for (int m = 0; m < 4; ++m) _Pragma("unroll") for (int n = 0; n < 2; ++n) _Pragma("unroll") for (int k = 0; k < 2; ++k) \
;         acc[ai][bj][m][n] = __builtin_amdgcn_mfma_f32_16x16x32_bf16(Bt[n][k], At[m][k], acc[ai][bj][m][n], 0, 0, 0); __builtin_amdgcn_s_setprio(0); } while (0)
; #define PG8_WAIT_V(n) asm volatile("s_waitcnt vmcnt(" #n ")" ::: "memory")
; #define PG8_WAIT_L(n) asm volatile("s_waitcnt lgkmcnt(" #n ")" ::: "memory")
; #define PG8_BAR __builtin_amdgcn_s_barrier()
; #define PG8_SCHED __builtin_amdgcn_sched_barrier(0)
; template <class Epi, class Sched>
; __device__ __forceinline__ void gemm_phase(LAS unsigned char* lds, const Gemm g, const Sched& S, const Epi& E) {
;     ...
;         for (int t = 0; t < nt; t += 2) {
;     ...
;             PG8_LDA(At, 1, 1); PG8_STAGE(PG8_SB(1, 0), b3, voffB); PG8_STAGE(PG8_SB(1, 1), b3 + hstepB, voffB); PG8_STAGE(PG8_SA(1, 0), a3, voffA);
;             PG8_WAIT_V(8); PG8_WAIT_L(0); PG8_BAR; PG8_MMA(1, 0, At, B0); PG8_MMA(1, 1, At, B1); PG8_BAR; PG8_SCHED;
;         }
	s_add_i32 s40, s60, s45
	v_lshl_add_u64 v[224:225], v[224:225], 0, s[36:37]
	s_mov_b32 m0, s40
	ds_read_b128 v[178:181], v161 offset:49152
	ds_read_b128 v[182:185], v161 offset:50176
	ds_read_b128 v[186:189], v161 offset:51200
	ds_read_b128 v[190:193], v161 offset:52224
	ds_read_b128 v[194:197], v161 offset:53248
	ds_read_b128 v[212:215], v161 offset:54272
	ds_read_b128 v[216:219], v161 offset:55296
	ds_read_b128 v[220:223], v161 offset:56320
	global_load_lds_dwordx4 v[224:225], off
	s_add_i32 m0, s40, 0x2000
	s_add_u32 s28, s28, 0x80080
	v_lshl_add_u64 v[224:225], v[226:227], 0, s[36:37]
	s_addc_u32 s29, s29, 0
	s_add_i32 s40, s61, s45
	global_load_lds_dwordx4 v[224:225], off
	v_lshl_add_u64 v[224:225], s[28:29], 0, v[4:5]
	s_mov_b32 m0, s40
	s_nop 0
	global_load_lds_dwordx4 v[224:225], off
	v_lshl_add_u64 v[224:225], s[28:29], 0, v[2:3]
	s_add_i32 m0, s40, 0x2000
	s_nop 0
	global_load_lds_dwordx4 v[224:225], off
	v_lshl_add_u64 v[224:225], v[228:229], 0, s[36:37]
	s_mov_b32 m0, s50
	s_nop 0
	global_load_lds_dwordx4 v[224:225], off
	v_lshl_add_u64 v[224:225], v[230:231], 0, s[36:37]
	s_mov_b32 m0, s51
	s_nop 0
	global_load_lds_dwordx4 v[224:225], off
	s_waitcnt vmcnt(8)
	s_waitcnt lgkmcnt(0)
	s_barrier
	s_setprio 1
	s_waitcnt lgkmcnt(0)
	v_mfma_f32_16x16x32_bf16 v[66:69], v[142:145], v[178:181], v[66:69]
	v_mfma_f32_16x16x32_bf16 v[58:61], v[150:153], v[178:181], v[58:61]
	v_mfma_f32_16x16x32_bf16 v[42:45], v[150:153], v[186:189], v[42:45]
	v_mfma_f32_16x16x32_bf16 v[50:53], v[142:145], v[186:189], v[50:53]
	v_mfma_f32_16x16x32_bf16 v[34:37], v[142:145], v[194:197], v[34:37]
	v_mfma_f32_16x16x32_bf16 v[26:29], v[150:153], v[194:197], v[26:29]
	v_mfma_f32_16x16x32_bf16 v[10:13], v[150:153], v[216:219], v[10:13]
	v_mfma_f32_16x16x32_bf16 v[18:21], v[142:145], v[216:219], v[18:21]
	v_mfma_f32_16x16x32_bf16 v[66:69], v[146:149], v[182:185], v[66:69]
	v_mfma_f32_16x16x32_bf16 v[58:61], v[154:157], v[182:185], v[58:61]
	v_mfma_f32_16x16x32_bf16 v[42:45], v[154:157], v[190:193], v[42:45]
	v_mfma_f32_16x16x32_bf16 v[50:53], v[146:149], v[190:193], v[50:53]
	v_mfma_f32_16x16x32_bf16 v[34:37], v[146:149], v[212:215], v[34:37]
	v_mfma_f32_16x16x32_bf16 v[26:29], v[154:157], v[212:215], v[26:29]
	v_mfma_f32_16x16x32_bf16 v[10:13], v[154:157], v[220:223], v[10:13]
	v_mfma_f32_16x16x32_bf16 v[18:21], v[146:149], v[220:223], v[18:21]
	s_setprio 0
	s_setprio 1
	v_mfma_f32_16x16x32_bf16 v[62:65], v[162:165], v[178:181], v[62:65]
	v_mfma_f32_16x16x32_bf16 v[54:57], v[170:173], v[178:181], v[54:57]
	v_mfma_f32_16x16x32_bf16 v[38:41], v[170:173], v[186:189], v[38:41]
	v_mfma_f32_16x16x32_bf16 v[46:49], v[162:165], v[186:189], v[46:49]
	v_mfma_f32_16x16x32_bf16 v[30:33], v[162:165], v[194:197], v[30:33]
	v_mfma_f32_16x16x32_bf16 v[22:25], v[170:173], v[194:197], v[22:25]
	v_mfma_f32_16x16x32_bf16 v[6:9], v[170:173], v[216:219], v[6:9]
	v_mfma_f32_16x16x32_bf16 v[14:17], v[162:165], v[216:219], v[14:17]
	v_mfma_f32_16x16x32_bf16 v[62:65], v[166:169], v[182:185], v[62:65]
	v_mfma_f32_16x16x32_bf16 v[54:57], v[174:177], v[182:185], v[54:57]
	v_mfma_f32_16x16x32_bf16 v[38:41], v[174:177], v[190:193], v[38:41]
	v_mfma_f32_16x16x32_bf16 v[46:49], v[166:169], v[190:193], v[46:49]
	v_mfma_f32_16x16x32_bf16 v[30:33], v[166:169], v[212:215], v[30:33]
	v_mfma_f32_16x16x32_bf16 v[22:25], v[174:177], v[212:215], v[22:25]
	v_mfma_f32_16x16x32_bf16 v[6:9], v[174:177], v[220:223], v[6:9]
	v_mfma_f32_16x16x32_bf16 v[14:17], v[166:169], v[220:223], v[14:17]
	s_setprio 0
	s_barrier
	s_add_i32 s59, s59, 2
	s_add_u32 s26, s26, 0x100
	s_addc_u32 s27, s27, 0
	s_add_u32 s57, s57, 0x100
	s_addc_u32 s58, s58, 0
	s_cmp_gt_u32 s59, 29
	s_cbranch_scc0 .LBB0_137
	s_and_b64 vcc, exec, s[16:17]
	s_cbranch_vccz .LBB0_140
	s_barrier

; #define PG8_STAGE(bufoff, gbase, voff) do { _Pragma("unroll") for (int _i = 0; _i < 2; ++_i) \
;         __builtin_amdgcn_global_load_lds((const unsigned*)((const char*)(gbase) + (voff)[_i]), (LAS unsigned*)(lds + (bufoff) + ldsw + _i * 8192), 16, 0, 0); } while (0)
; #define PG8_LDA(dst, b, h) do { _Pragma("unroll") for (int m = 0; m < 4; ++m) _Pragma("unroll") for (int k = 0; k < 2; ++k) dst[m][k] = *(const LAS bf16x8*)(lds + PG8_SA(b, h) + aoff + m * 2048 + k * 1024); } while (0)
; #define PG8_LDB(dst, b, h) do { _Pragma("unroll") for (int n = 0; n < 2; ++n) _Pragma("unroll") for (int k = 0; k < 2; ++k) dst[n][k] = *(const LAS bf16x8*)(lds + PG8_SB(b, h) + boff + n * 2048 + k * 1024); } while (0)
; #define PG8_MMA(ai, bj, At, Bt) do { __builtin_amdgcn_s_setprio(1); _Pragma("unroll") for (int m = 0; m < 4; ++m) _Pragma("unroll") for (int n = 0; n < 2; ++n) _Pragma("unroll") for (int k = 0; k < 2; ++k) \
;         acc[ai][bj][m][n] = __builtin_amdgcn_mfma_f32_16x16x32_bf16(Bt[n][k], At[m][k], acc[ai][bj][m][n], 0, 0, 0); __builtin_amdgcn_s_setprio(0); } while (0)
; #define PG8_WAIT_V(n) asm volatile("s_waitcnt vmcnt(" #n ")" ::: "memory")
; #define PG8_WAIT_L(n) asm volatile("s_waitcnt lgkmcnt(" #n ")" ::: "memory")
; #define PG8_BAR __builtin_amdgcn_s_barrier()
; #define PG8_SCHED __builtin_amdgcn_sched_barrier(0)
; template <class Epi, class Sched>
; __device__ __forceinline__ void gemm_phase(LAS unsigned char* lds, const Gemm g, const Sched& S, const Epi& E) {
;     ...
;             PG8_LDB(B0, 0, 0); PG8_LDB(B1, 0, 1); PG8_SCHED; PG8_LDA(At, 0, 0); PG8_STAGE(PG8_SA(1, 1), a1 + hstepA, voffA);
;             PG8_WAIT_V(8); PG8_WAIT_L(0); PG8_BAR; PG8_MMA(0, 0, At, B0); PG8_MMA(0, 1, At, B1); PG8_BAR; PG8_SCHED;
;             PG8_LDA(At, 0, 1); PG8_STAGE(PG8_SB(0, 0), b2, voffB); PG8_STAGE(PG8_SB(0, 1), b2 + hstepB, voffB); PG8_STAGE(PG8_SA(0, 0), a2, voffA);
.LBB0_281:
	s_add_u32 s26, s20, s24
	s_addc_u32 s27, s21, s25
	s_add_u32 s26, s26, 0x100
	s_addc_u32 s27, s27, 0
	s_add_u32 s63, s60, s24
	s_addc_u32 s65, s61, s25
	s_add_i32 s67, 0, 0x10000
	s_cmpk_eq_i32 s24, 0x2a00
	s_cselect_b32 s29, s5, s27
	s_cselect_b32 s28, s4, s26
	s_cselect_b32 s27, s23, s65
	s_cselect_b32 s26, s22, s63
	s_add_i32 s63, 0, 0x14000
	v_add_u32_e32 v158, s67, v144
	v_add_u32_e32 v174, s63, v144
	ds_read_b128 v[146:149], v158
	ds_read_b128 v[150:153], v158 offset:1024
	ds_read_b128 v[154:157], v158 offset:2048
	ds_read_b128 v[158:161], v158 offset:3072
	ds_read_b128 v[162:165], v174
	ds_read_b128 v[166:169], v174 offset:1024
	ds_read_b128 v[170:173], v174 offset:2048
	ds_read_b128 v[174:177], v174 offset:3072
	v_lshl_add_u64 v[224:225], v[138:139], 0, s[24:25]
	s_add_i32 m0, s50, 0xc000
	ds_read_b128 v[178:181], v145
	ds_read_b128 v[182:185], v145 offset:1024
	ds_read_b128 v[186:189], v145 offset:2048
	ds_read_b128 v[190:193], v145 offset:3072
	ds_read_b128 v[194:197], v145 offset:4096
	ds_read_b128 v[212:215], v145 offset:5120
	ds_read_b128 v[216:219], v145 offset:6144
	ds_read_b128 v[220:223], v145 offset:7168
	global_load_lds_dwordx4 v[224:225], off
	v_lshl_add_u64 v[224:225], v[140:141], 0, s[24:25]
	s_add_i32 m0, s50, 0xe000
	s_nop 0
	global_load_lds_dwordx4 v[224:225], off
	s_waitcnt vmcnt(8)
	s_waitcnt lgkmcnt(0)
	s_barrier
	s_setprio 1
	s_waitcnt lgkmcnt(0)
	v_mfma_f32_16x16x32_bf16 v[130:133], v[146:149], v[178:181], v[130:133]
	v_mfma_f32_16x16x32_bf16 v[126:129], v[154:157], v[178:181], v[126:129]
	v_mfma_f32_16x16x32_bf16 v[118:121], v[154:157], v[186:189], v[118:121]
	v_mfma_f32_16x16x32_bf16 v[122:125], v[146:149], v[186:189], v[122:125]
	v_mfma_f32_16x16x32_bf16 v[110:113], v[146:149], v[194:197], v[110:113]
	v_mfma_f32_16x16x32_bf16 v[106:109], v[154:157], v[194:197], v[106:109]
	v_mfma_f32_16x16x32_bf16 v[90:93], v[154:157], v[216:219], v[90:93]
	v_mfma_f32_16x16x32_bf16 v[98:101], v[146:149], v[216:219], v[98:101]
	v_mfma_f32_16x16x32_bf16 v[130:133], v[150:153], v[182:185], v[130:133]
	v_mfma_f32_16x16x32_bf16 v[126:129], v[158:161], v[182:185], v[126:129]
	v_mfma_f32_16x16x32_bf16 v[118:121], v[158:161], v[190:193], v[118:121]
	v_mfma_f32_16x16x32_bf16 v[122:125], v[150:153], v[190:193], v[122:125]
	v_mfma_f32_16x16x32_bf16 v[110:113], v[150:153], v[212:215], v[110:113]
	v_mfma_f32_16x16x32_bf16 v[106:109], v[158:161], v[212:215], v[106:109]
	v_mfma_f32_16x16x32_bf16 v[90:93], v[158:161], v[220:223], v[90:93]
	v_mfma_f32_16x16x32_bf16 v[98:101], v[150:153], v[220:223], v[98:101]
	s_setprio 0
	s_setprio 1
	v_mfma_f32_16x16x32_bf16 v[114:117], v[162:165], v[178:181], v[114:117]
	v_mfma_f32_16x16x32_bf16 v[102:105], v[170:173], v[178:181], v[102:105]
	v_mfma_f32_16x16x32_bf16 v[86:89], v[170:173], v[186:189], v[86:89]
	v_mfma_f32_16x16x32_bf16 v[94:97], v[162:165], v[186:189], v[94:97]
	v_mfma_f32_16x16x32_bf16 v[82:85], v[162:165], v[194:197], v[82:85]
	v_mfma_f32_16x16x32_bf16 v[78:81], v[170:173], v[194:197], v[78:81]
	v_mfma_f32_16x16x32_bf16 v[70:73], v[170:173], v[216:219], v[70:73]
	v_mfma_f32_16x16x32_bf16 v[74:77], v[162:165], v[216:219], v[74:77]
	v_mfma_f32_16x16x32_bf16 v[114:117], v[166:169], v[182:185], v[114:117]
	v_mfma_f32_16x16x32_bf16 v[102:105], v[174:177], v[182:185], v[102:105]
	v_mfma_f32_16x16x32_bf16 v[86:89], v[174:177], v[190:193], v[86:89]
	v_mfma_f32_16x16x32_bf16 v[94:97], v[166:169], v[190:193], v[94:97]
	v_mfma_f32_16x16x32_bf16 v[82:85], v[166:169], v[212:215], v[82:85]
	v_mfma_f32_16x16x32_bf16 v[78:81], v[174:177], v[212:215], v[78:81]
	v_mfma_f32_16x16x32_bf16 v[70:73], v[174:177], v[220:223], v[70:73]
	v_mfma_f32_16x16x32_bf16 v[74:77], v[166:169], v[220:223], v[74:77]
	s_setprio 0
	s_barrier
	s_add_i32 s65, s67, s11
	v_lshl_add_u64 v[224:225], s[26:27], 0, v[4:5]
	s_mov_b32 m0, s65
	ds_read_b128 v[178:181], v145 offset:16384
	ds_read_b128 v[182:185], v145 offset:17408
	ds_read_b128 v[186:189], v145 offset:18432
	ds_read_b128 v[190:193], v145 offset:19456
	ds_read_b128 v[194:197], v145 offset:20480
	ds_read_b128 v[212:215], v145 offset:21504
	ds_read_b128 v[216:219], v145 offset:22528
	ds_read_b128 v[220:223], v145 offset:23552
	global_load_lds_dwordx4 v[224:225], off
	s_add_i32 m0, s65, 0x2000
	s_add_u32 s68, s26, 0x158000
	v_lshl_add_u64 v[226:227], s[26:27], 0, v[2:3]
	s_addc_u32 s69, s27, 0
	s_add_i32 s63, s63, s11
	global_load_lds_dwordx4 v[226:227], off
	v_lshl_add_u64 v[228:229], s[68:69], 0, v[4:5]
	s_mov_b32 m0, s63
	v_lshl_add_u64 v[230:231], s[28:29], 0, v[2:3]
	global_load_lds_dwordx4 v[228:229], off
	v_lshl_add_u64 v[228:229], s[68:69], 0, v[2:3]
	s_add_i32 m0, s63, 0x2000
	s_nop 0
	global_load_lds_dwordx4 v[228:229], off
	v_lshl_add_u64 v[228:229], s[28:29], 0, v[4:5]
	s_mov_b32 m0, s50
	s_nop 0
	global_load_lds_dwordx4 v[228:229], off
	s_mov_b32 m0, s51
	s_nop 0
	global_load_lds_dwordx4 v[230:231], off
	s_waitcnt vmcnt(8)
	s_waitcnt lgkmcnt(0)
	s_barrier
; #define PG8_STAGE(bufoff, gbase, voff) do { _Pragma("unroll") for (int _i = 0; _i < 2; ++_i) \
;         __builtin_amdgcn_global_load_lds((const unsigned*)((const char*)(gbase) + (voff)[_i]), (LAS unsigned*)(lds + (bufoff) + ldsw + _i * 8192), 16, 0, 0); } while (0)
; #define PG8_LDA(dst, b, h) do { _Pragma("unroll") for (int m = 0; m < 4; ++m) _Pragma("unroll") for (int k = 0; k < 2; ++k) dst[m][k] = *(const LAS bf16x8*)(lds + PG8_SA(b, h) + aoff + m * 2048 + k * 1024); } while (0)
; #define PG8_LDB(dst, b, h) do { _Pragma("unroll") for (int n = 0; n < 2; ++n) _Pragma("unroll") for (int k = 0; k < 2; ++k) dst[n][k] = *(const LAS bf16x8*)(lds + PG8_SB(b, h) + boff + n * 2048 + k * 1024); } while (0)
; #define PG8_MMA(ai, bj, At, Bt) do { __builtin_amdgcn_s_setprio(1); _Pragma("unroll") for (int m = 0; m < 4; ++m) _Pragma("unroll") for (int n = 0; n < 2; ++n) _Pragma("unroll") for (int k = 0; k < 2; ++k) \
;         acc[ai][bj][m][n] = __builtin_amdgcn_mfma_f32_16x16x32_bf16(Bt[n][k], At[m][k], acc[ai][bj][m][n], 0, 0, 0); __builtin_amdgcn_s_setprio(0); } while (0)
; #define PG8_WAIT_V(n) asm volatile("s_waitcnt vmcnt(" #n ")" ::: "memory")
; #define PG8_WAIT_L(n) asm volatile("s_waitcnt lgkmcnt(" #n ")" ::: "memory")
; #define PG8_BAR __builtin_amdgcn_s_barrier()
; #define PG8_SCHED __builtin_amdgcn_sched_barrier(0)
; template <class Epi, class Sched>
; __device__ __forceinline__ void gemm_phase(LAS unsigned char* lds, const Gemm g, const Sched& S, const Epi& E) {
;     ...
;             PG8_WAIT_V(8); PG8_WAIT_L(0); PG8_BAR; PG8_MMA(1, 0, At, B0); PG8_MMA(1, 1, At, B1); PG8_BAR; PG8_SCHED;
;             PG8_LDB(B0, 1, 0); PG8_LDB(B1, 1, 1); PG8_SCHED; PG8_LDA(At, 1, 0); PG8_STAGE(PG8_SA(0, 1), a2 + hstepA, voffA);
;             PG8_WAIT_V(8); PG8_WAIT_L(0); PG8_BAR; PG8_MMA(0, 0, At, B0); PG8_MMA(0, 1, At, B1); PG8_BAR; PG8_SCHED;
	s_setprio 1
	s_waitcnt lgkmcnt(0)
	v_mfma_f32_16x16x32_bf16 v[66:69], v[146:149], v[178:181], v[66:69]
	v_mfma_f32_16x16x32_bf16 v[62:65], v[154:157], v[178:181], v[62:65]
	v_mfma_f32_16x16x32_bf16 v[54:57], v[154:157], v[186:189], v[54:57]
	v_mfma_f32_16x16x32_bf16 v[58:61], v[146:149], v[186:189], v[58:61]
	v_mfma_f32_16x16x32_bf16 v[50:53], v[146:149], v[194:197], v[50:53]
	v_mfma_f32_16x16x32_bf16 v[42:45], v[154:157], v[194:197], v[42:45]
	v_mfma_f32_16x16x32_bf16 v[26:29], v[154:157], v[216:219], v[26:29]
	v_mfma_f32_16x16x32_bf16 v[34:37], v[146:149], v[216:219], v[34:37]
	v_mfma_f32_16x16x32_bf16 v[66:69], v[150:153], v[182:185], v[66:69]
	v_mfma_f32_16x16x32_bf16 v[62:65], v[158:161], v[182:185], v[62:65]
	v_mfma_f32_16x16x32_bf16 v[54:57], v[158:161], v[190:193], v[54:57]
	v_mfma_f32_16x16x32_bf16 v[58:61], v[150:153], v[190:193], v[58:61]
	v_mfma_f32_16x16x32_bf16 v[50:53], v[150:153], v[212:215], v[50:53]
	v_mfma_f32_16x16x32_bf16 v[42:45], v[158:161], v[212:215], v[42:45]
	v_mfma_f32_16x16x32_bf16 v[26:29], v[158:161], v[220:223], v[26:29]
	v_mfma_f32_16x16x32_bf16 v[34:37], v[150:153], v[220:223], v[34:37]
	s_setprio 0
	s_setprio 1
	v_mfma_f32_16x16x32_bf16 v[46:49], v[162:165], v[178:181], v[46:49]
	v_mfma_f32_16x16x32_bf16 v[38:41], v[170:173], v[178:181], v[38:41]
	v_mfma_f32_16x16x32_bf16 v[22:25], v[170:173], v[186:189], v[22:25]
	v_mfma_f32_16x16x32_bf16 v[30:33], v[162:165], v[186:189], v[30:33]
	v_mfma_f32_16x16x32_bf16 v[18:21], v[162:165], v[194:197], v[18:21]
	v_mfma_f32_16x16x32_bf16 v[14:17], v[170:173], v[194:197], v[14:17]
	v_mfma_f32_16x16x32_bf16 v[6:9], v[170:173], v[216:219], v[6:9]
	v_mfma_f32_16x16x32_bf16 v[10:13], v[162:165], v[216:219], v[10:13]
	v_mfma_f32_16x16x32_bf16 v[46:49], v[166:169], v[182:185], v[46:49]
	v_mfma_f32_16x16x32_bf16 v[38:41], v[174:177], v[182:185], v[38:41]
	v_mfma_f32_16x16x32_bf16 v[22:25], v[174:177], v[190:193], v[22:25]
	v_mfma_f32_16x16x32_bf16 v[30:33], v[166:169], v[190:193], v[30:33]
	v_mfma_f32_16x16x32_bf16 v[18:21], v[166:169], v[212:215], v[18:21]
	v_mfma_f32_16x16x32_bf16 v[14:17], v[174:177], v[212:215], v[14:17]
	v_mfma_f32_16x16x32_bf16 v[6:9], v[174:177], v[220:223], v[6:9]
	v_mfma_f32_16x16x32_bf16 v[10:13], v[166:169], v[220:223], v[10:13]
	s_setprio 0
	s_barrier
	s_add_i32 s63, 0, 0x18000
	s_add_i32 s65, 0, 0x1c000
	v_add_u32_e32 v158, s63, v144
	v_add_u32_e32 v174, s65, v144
	ds_read_b128 v[146:149], v158
	ds_read_b128 v[150:153], v158 offset:1024
	ds_read_b128 v[154:157], v158 offset:2048
	ds_read_b128 v[158:161], v158 offset:3072
	ds_read_b128 v[162:165], v174
	ds_read_b128 v[166:169], v174 offset:1024
	ds_read_b128 v[170:173], v174 offset:2048
	ds_read_b128 v[174:177], v174 offset:3072
	s_add_u32 s28, s28, 0x158000
	s_addc_u32 s29, s29, 0
	s_mov_b32 m0, s52
	v_lshl_add_u64 v[236:237], s[28:29], 0, v[4:5]
	ds_read_b128 v[178:181], v145 offset:32768
	ds_read_b128 v[182:185], v145 offset:33792
	ds_read_b128 v[186:189], v145 offset:34816
	ds_read_b128 v[190:193], v145 offset:35840
	ds_read_b128 v[194:197], v145 offset:36864
	ds_read_b128 v[212:215], v145 offset:37888
	ds_read_b128 v[216:219], v145 offset:38912
	ds_read_b128 v[220:223], v145 offset:39936
	global_load_lds_dwordx4 v[236:237], off
	v_lshl_add_u64 v[236:237], s[28:29], 0, v[2:3]
	s_mov_b32 m0, s53
	s_nop 0
	global_load_lds_dwordx4 v[236:237], off
	s_waitcnt vmcnt(8)
	s_waitcnt lgkmcnt(0)
	s_barrier
	s_setprio 1
	s_waitcnt lgkmcnt(0)
	v_mfma_f32_16x16x32_bf16 v[130:133], v[146:149], v[178:181], v[130:133]
	v_mfma_f32_16x16x32_bf16 v[126:129], v[154:157], v[178:181], v[126:129]
	v_mfma_f32_16x16x32_bf16 v[118:121], v[154:157], v[186:189], v[118:121]
	v_mfma_f32_16x16x32_bf16 v[122:125], v[146:149], v[186:189], v[122:125]
	v_mfma_f32_16x16x32_bf16 v[110:113], v[146:149], v[194:197], v[110:113]
	v_mfma_f32_16x16x32_bf16 v[106:109], v[154:157], v[194:197], v[106:109]
	v_mfma_f32_16x16x32_bf16 v[90:93], v[154:157], v[216:219], v[90:93]
	v_mfma_f32_16x16x32_bf16 v[98:101], v[146:149], v[216:219], v[98:101]
	v_mfma_f32_16x16x32_bf16 v[130:133], v[150:153], v[182:185], v[130:133]
	v_mfma_f32_16x16x32_bf16 v[126:129], v[158:161], v[182:185], v[126:129]
	v_mfma_f32_16x16x32_bf16 v[118:121], v[158:161], v[190:193], v[118:121]
	v_mfma_f32_16x16x32_bf16 v[122:125], v[150:153], v[190:193], v[122:125]
	v_mfma_f32_16x16x32_bf16 v[110:113], v[150:153], v[212:215], v[110:113]
	v_mfma_f32_16x16x32_bf16 v[106:109], v[158:161], v[212:215], v[106:109]
	v_mfma_f32_16x16x32_bf16 v[90:93], v[158:161], v[220:223], v[90:93]
	v_mfma_f32_16x16x32_bf16 v[98:101], v[150:153], v[220:223], v[98:101]
	s_setprio 0
	s_setprio 1
	v_mfma_f32_16x16x32_bf16 v[114:117], v[162:165], v[178:181], v[114:117]
	v_mfma_f32_16x16x32_bf16 v[102:105], v[170:173], v[178:181], v[102:105]
	v_mfma_f32_16x16x32_bf16 v[86:89], v[170:173], v[186:189], v[86:89]
	v_mfma_f32_16x16x32_bf16 v[94:97], v[162:165], v[186:189], v[94:97]
	v_mfma_f32_16x16x32_bf16 v[82:85], v[162:165], v[194:197], v[82:85]
	v_mfma_f32_16x16x32_bf16 v[78:81], v[170:173], v[194:197], v[78:81]
	v_mfma_f32_16x16x32_bf16 v[70:73], v[170:173], v[216:219], v[70:73]
	v_mfma_f32_16x16x32_bf16 v[74:77], v[162:165], v[216:219], v[74:77]
	v_mfma_f32_16x16x32_bf16 v[114:117], v[166:169], v[182:185], v[114:117]
	v_mfma_f32_16x16x32_bf16 v[102:105], v[174:177], v[182:185], v[102:105]
	v_mfma_f32_16x16x32_bf16 v[86:89], v[174:177], v[190:193], v[86:89]
	v_mfma_f32_16x16x32_bf16 v[94:97], v[166:169], v[190:193], v[94:97]
	v_mfma_f32_16x16x32_bf16 v[82:85], v[166:169], v[212:215], v[82:85]
	v_mfma_f32_16x16x32_bf16 v[78:81], v[174:177], v[212:215], v[78:81]
	v_mfma_f32_16x16x32_bf16 v[70:73], v[174:177], v[220:223], v[70:73]
	v_mfma_f32_16x16x32_bf16 v[74:77], v[166:169], v[220:223], v[74:77]
	s_setprio 0
	s_barrier
; #define PG8_STAGE(bufoff, gbase, voff) do { _Pragma("unroll") for (int _i = 0; _i < 2; ++_i) \
;         __builtin_amdgcn_global_load_lds((const unsigned*)((const char*)(gbase) + (voff)[_i]), (LAS unsigned*)(lds + (bufoff) + ldsw + _i * 8192), 16, 0, 0); } while (0)
; #define PG8_LDA(dst, b, h) do { _Pragma("unroll") for (int m = 0; m < 4; ++m) _Pragma("unroll") for (int k = 0; k < 2; ++k) dst[m][k] = *(const LAS bf16x8*)(lds + PG8_SA(b, h) + aoff + m * 2048 + k * 1024); } while (0)
; #define PG8_MMA(ai, bj, At, Bt) do { __builtin_amdgcn_s_setprio(1); _Pragma("unroll") for (int m = 0; m < 4; ++m) _Pragma("unroll") for (int n = 0; n < 2; ++n) _Pragma("unroll") for (int k = 0; k < 2; ++k) \
;         acc[ai][bj][m][n] = __builtin_amdgcn_mfma_f32_16x16x32_bf16(Bt[n][k], At[m][k], acc[ai][bj][m][n], 0, 0, 0); __builtin_amdgcn_s_setprio(0); } while (0)
; #define PG8_WAIT_V(n) asm volatile("s_waitcnt vmcnt(" #n ")" ::: "memory")
; #define PG8_WAIT_L(n) asm volatile("s_waitcnt lgkmcnt(" #n ")" ::: "memory")
; #define PG8_BAR __builtin_amdgcn_s_barrier()
; #define PG8_SCHED __builtin_amdgcn_sched_barrier(0)
; template <class Epi, class Sched>
; __device__ __forceinline__ void gemm_phase(LAS unsigned char* lds, const Gemm g, const Sched& S, const Epi& E) {
;     ...
;         for (int t = 0; t < nt; t += 2) {
;     ...
;             PG8_LDA(At, 1, 1); PG8_STAGE(PG8_SB(1, 0), b3, voffB); PG8_STAGE(PG8_SB(1, 1), b3 + hstepB, voffB); PG8_STAGE(PG8_SA(1, 0), a3, voffA);
;             PG8_WAIT_V(8); PG8_WAIT_L(0); PG8_BAR; PG8_MMA(1, 0, At, B0); PG8_MMA(1, 1, At, B1); PG8_BAR; PG8_SCHED;
;         }
	s_add_i32 s28, s63, s11
	v_lshl_add_u64 v[224:225], v[224:225], 0, s[36:37]
	s_mov_b32 m0, s28
	ds_read_b128 v[178:181], v145 offset:49152
	ds_read_b128 v[182:185], v145 offset:50176
	ds_read_b128 v[186:189], v145 offset:51200
	ds_read_b128 v[190:193], v145 offset:52224
	ds_read_b128 v[194:197], v145 offset:53248
	ds_read_b128 v[212:215], v145 offset:54272
	ds_read_b128 v[216:219], v145 offset:55296
	ds_read_b128 v[220:223], v145 offset:56320
	global_load_lds_dwordx4 v[224:225], off
	s_add_i32 m0, s28, 0x2000
	s_add_u32 s26, s26, 0x158080
	v_lshl_add_u64 v[224:225], v[226:227], 0, s[36:37]
	s_addc_u32 s27, s27, 0
	s_add_i32 s28, s65, s11
	global_load_lds_dwordx4 v[224:225], off
	v_lshl_add_u64 v[224:225], s[26:27], 0, v[4:5]
	s_mov_b32 m0, s28
	s_nop 0
	global_load_lds_dwordx4 v[224:225], off
	v_lshl_add_u64 v[224:225], s[26:27], 0, v[2:3]
	s_add_i32 m0, s28, 0x2000
	s_nop 0
	global_load_lds_dwordx4 v[224:225], off
	v_lshl_add_u64 v[224:225], v[228:229], 0, s[36:37]
	s_mov_b32 m0, s54
	s_nop 0
	global_load_lds_dwordx4 v[224:225], off
	v_lshl_add_u64 v[224:225], v[230:231], 0, s[36:37]
	s_mov_b32 m0, s55
	s_nop 0
	global_load_lds_dwordx4 v[224:225], off
	s_waitcnt vmcnt(8)
	s_waitcnt lgkmcnt(0)
	s_barrier
	s_setprio 1
	s_waitcnt lgkmcnt(0)
	v_mfma_f32_16x16x32_bf16 v[66:69], v[146:149], v[178:181], v[66:69]
	v_mfma_f32_16x16x32_bf16 v[62:65], v[154:157], v[178:181], v[62:65]
	v_mfma_f32_16x16x32_bf16 v[54:57], v[154:157], v[186:189], v[54:57]
	v_mfma_f32_16x16x32_bf16 v[58:61], v[146:149], v[186:189], v[58:61]
	v_mfma_f32_16x16x32_bf16 v[50:53], v[146:149], v[194:197], v[50:53]
	v_mfma_f32_16x16x32_bf16 v[42:45], v[154:157], v[194:197], v[42:45]
	v_mfma_f32_16x16x32_bf16 v[26:29], v[154:157], v[216:219], v[26:29]
	v_mfma_f32_16x16x32_bf16 v[34:37], v[146:149], v[216:219], v[34:37]
	v_mfma_f32_16x16x32_bf16 v[66:69], v[150:153], v[182:185], v[66:69]
	v_mfma_f32_16x16x32_bf16 v[62:65], v[158:161], v[182:185], v[62:65]
	v_mfma_f32_16x16x32_bf16 v[54:57], v[158:161], v[190:193], v[54:57]
	v_mfma_f32_16x16x32_bf16 v[58:61], v[150:153], v[190:193], v[58:61]
	v_mfma_f32_16x16x32_bf16 v[50:53], v[150:153], v[212:215], v[50:53]
	v_mfma_f32_16x16x32_bf16 v[42:45], v[158:161], v[212:215], v[42:45]
	v_mfma_f32_16x16x32_bf16 v[26:29], v[158:161], v[220:223], v[26:29]
	v_mfma_f32_16x16x32_bf16 v[34:37], v[150:153], v[220:223], v[34:37]
	s_setprio 0
	s_setprio 1
	v_mfma_f32_16x16x32_bf16 v[46:49], v[162:165], v[178:181], v[46:49]
	v_mfma_f32_16x16x32_bf16 v[38:41], v[170:173], v[178:181], v[38:41]
	v_mfma_f32_16x16x32_bf16 v[22:25], v[170:173], v[186:189], v[22:25]
	v_mfma_f32_16x16x32_bf16 v[30:33], v[162:165], v[186:189], v[30:33]
	v_mfma_f32_16x16x32_bf16 v[18:21], v[162:165], v[194:197], v[18:21]
	v_mfma_f32_16x16x32_bf16 v[14:17], v[170:173], v[194:197], v[14:17]
	v_mfma_f32_16x16x32_bf16 v[6:9], v[170:173], v[216:219], v[6:9]
	v_mfma_f32_16x16x32_bf16 v[10:13], v[162:165], v[216:219], v[10:13]
	v_mfma_f32_16x16x32_bf16 v[46:49], v[166:169], v[182:185], v[46:49]
	v_mfma_f32_16x16x32_bf16 v[38:41], v[174:177], v[182:185], v[38:41]
	v_mfma_f32_16x16x32_bf16 v[22:25], v[174:177], v[190:193], v[22:25]
	v_mfma_f32_16x16x32_bf16 v[30:33], v[166:169], v[190:193], v[30:33]
	v_mfma_f32_16x16x32_bf16 v[18:21], v[166:169], v[212:215], v[18:21]
	v_mfma_f32_16x16x32_bf16 v[14:17], v[174:177], v[212:215], v[14:17]
	v_mfma_f32_16x16x32_bf16 v[6:9], v[174:177], v[220:223], v[6:9]
	v_mfma_f32_16x16x32_bf16 v[10:13], v[166:169], v[220:223], v[10:13]
	s_setprio 0
	s_barrier
	s_add_i32 s62, s62, 2
	s_add_u32 s24, s24, 0x100
	s_addc_u32 s25, s25, 0
	s_cmpk_gt_u32 s62, 0x53
	s_cbranch_scc0 .LBB0_281
	s_and_b64 vcc, exec, s[18:19]
	s_cbranch_vccz .LBB0_284
	s_barrier

; #define PG8_STAGE(bufoff, gbase, voff) do { _Pragma("unroll") for (int _i = 0; _i < 2; ++_i) \
;         __builtin_amdgcn_global_load_lds((const unsigned*)((const char*)(gbase) + (voff)[_i]), (LAS unsigned*)(lds + (bufoff) + ldsw + _i * 8192), 16, 0, 0); } while (0)
; #define PG8_LDA(dst, b, h) do { _Pragma("unroll") for (int m = 0; m < 4; ++m) _Pragma("unroll") for (int k = 0; k < 2; ++k) dst[m][k] = *(const LAS bf16x8*)(lds + PG8_SA(b, h) + aoff + m * 2048 + k * 1024); } while (0)
; #define PG8_LDB(dst, b, h) do { _Pragma("unroll") for (int n = 0; n < 2; ++n) _Pragma("unroll") for (int k = 0; k < 2; ++k) dst[n][k] = *(const LAS bf16x8*)(lds + PG8_SB(b, h) + boff + n * 2048 + k * 1024); } while (0)
; #define PG8_MMA(ai, bj, At, Bt) do { __builtin_amdgcn_s_setprio(1); _Pragma("unroll") for (int m = 0; m < 4; ++m) _Pragma("unroll") for (int n = 0; n < 2; ++n) _Pragma("unroll") for (int k = 0; k < 2; ++k) \
;         acc[ai][bj][m][n] = __builtin_amdgcn_mfma_f32_16x16x32_bf16(Bt[n][k], At[m][k], acc[ai][bj][m][n], 0, 0, 0); __builtin_amdgcn_s_setprio(0); } while (0)
; #define PG8_WAIT_V(n) asm volatile("s_waitcnt vmcnt(" #n ")" ::: "memory")
; #define PG8_WAIT_L(n) asm volatile("s_waitcnt lgkmcnt(" #n ")" ::: "memory")
; #define PG8_BAR __builtin_amdgcn_s_barrier()
; #define PG8_SCHED __builtin_amdgcn_sched_barrier(0)
; template <class Epi, class Sched>
; __device__ __forceinline__ void gemm_phase(LAS unsigned char* lds, const Gemm g, const Sched& S, const Epi& E) {
;     ...
;             PG8_LDB(B0, 0, 0); PG8_LDB(B1, 0, 1); PG8_SCHED; PG8_LDA(At, 0, 0); PG8_STAGE(PG8_SA(1, 1), a1 + hstepA, voffA);
;             PG8_WAIT_V(8); PG8_WAIT_L(0); PG8_BAR; PG8_MMA(0, 0, At, B0); PG8_MMA(0, 1, At, B1); PG8_BAR; PG8_SCHED;
;             PG8_LDA(At, 0, 1); PG8_STAGE(PG8_SB(0, 0), b2, voffB); PG8_STAGE(PG8_SB(0, 1), b2 + hstepB, voffB); PG8_STAGE(PG8_SA(0, 0), a2, voffA);
.LBB0_513:
	s_add_u32 s42, s38, 0xfff80080
	s_addc_u32 s43, s39, -1
	s_add_i32 s61, 0, 0x10000
	s_cmp_eq_u32 s60, 28
	s_cselect_b32 s45, s21, s43
	s_cselect_b32 s44, s27, s42
	s_cselect_b32 s43, s19, s59
	s_cselect_b32 s42, s29, s58
	s_add_i32 s64, 0, 0x14000
	v_add_u32_e32 v98, s61, v236
	v_add_u32_e32 v162, s64, v236
	ds_read_b128 v[86:89], v98
	ds_read_b128 v[90:93], v98 offset:1024
	ds_read_b128 v[94:97], v98 offset:2048
	ds_read_b128 v[98:101], v98 offset:3072
	ds_read_b128 v[150:153], v162
	ds_read_b128 v[154:157], v162 offset:1024
	ds_read_b128 v[158:161], v162 offset:2048
	ds_read_b128 v[162:165], v162 offset:3072
	v_lshl_add_u64 v[228:229], s[38:39], 0, v[224:225]
	s_add_i32 m0, s50, 0xc000
	ds_read_b128 v[166:169], v237
	ds_read_b128 v[170:173], v237 offset:1024
	ds_read_b128 v[174:177], v237 offset:2048
	ds_read_b128 v[178:181], v237 offset:3072
	ds_read_b128 v[182:185], v237 offset:4096
	ds_read_b128 v[186:189], v237 offset:5120
	ds_read_b128 v[190:193], v237 offset:6144
	ds_read_b128 v[194:197], v237 offset:7168
	global_load_lds_dwordx4 v[228:229], off
	v_lshl_add_u64 v[228:229], s[38:39], 0, v[226:227]
	s_add_i32 m0, s50, 0xe000
	s_nop 0
	global_load_lds_dwordx4 v[228:229], off
	s_waitcnt vmcnt(8)
	s_waitcnt lgkmcnt(0)
	s_barrier
	s_setprio 1
	s_waitcnt lgkmcnt(0)
	v_mfma_f32_16x16x32_bf16 v[146:149], v[86:89], v[166:169], v[146:149]
	v_mfma_f32_16x16x32_bf16 v[142:145], v[94:97], v[166:169], v[142:145]
	v_mfma_f32_16x16x32_bf16 v[126:129], v[94:97], v[174:177], v[126:129]
	v_mfma_f32_16x16x32_bf16 v[130:133], v[86:89], v[174:177], v[130:133]
	v_mfma_f32_16x16x32_bf16 v[114:117], v[86:89], v[182:185], v[114:117]
	v_mfma_f32_16x16x32_bf16 v[110:113], v[94:97], v[182:185], v[110:113]
	v_mfma_f32_16x16x32_bf16 v[78:81], v[94:97], v[190:193], v[78:81]
	v_mfma_f32_16x16x32_bf16 v[82:85], v[86:89], v[190:193], v[82:85]
	v_mfma_f32_16x16x32_bf16 v[146:149], v[90:93], v[170:173], v[146:149]
	v_mfma_f32_16x16x32_bf16 v[142:145], v[98:101], v[170:173], v[142:145]
	v_mfma_f32_16x16x32_bf16 v[126:129], v[98:101], v[178:181], v[126:129]
	v_mfma_f32_16x16x32_bf16 v[130:133], v[90:93], v[178:181], v[130:133]
	v_mfma_f32_16x16x32_bf16 v[114:117], v[90:93], v[186:189], v[114:117]
	v_mfma_f32_16x16x32_bf16 v[110:113], v[98:101], v[186:189], v[110:113]
	v_mfma_f32_16x16x32_bf16 v[78:81], v[98:101], v[194:197], v[78:81]
	v_mfma_f32_16x16x32_bf16 v[82:85], v[90:93], v[194:197], v[82:85]
	s_setprio 0
	s_setprio 1
	v_mfma_f32_16x16x32_bf16 v[138:141], v[150:153], v[166:169], v[138:141]
	v_mfma_f32_16x16x32_bf16 v[134:137], v[158:161], v[166:169], v[134:137]
	v_mfma_f32_16x16x32_bf16 v[118:121], v[158:161], v[174:177], v[118:121]
	v_mfma_f32_16x16x32_bf16 v[122:125], v[150:153], v[174:177], v[122:125]
	v_mfma_f32_16x16x32_bf16 v[106:109], v[150:153], v[182:185], v[106:109]
	v_mfma_f32_16x16x32_bf16 v[102:105], v[158:161], v[182:185], v[102:105]
	v_mfma_f32_16x16x32_bf16 v[70:73], v[158:161], v[190:193], v[70:73]
	v_mfma_f32_16x16x32_bf16 v[74:77], v[150:153], v[190:193], v[74:77]
	v_mfma_f32_16x16x32_bf16 v[138:141], v[154:157], v[170:173], v[138:141]
	v_mfma_f32_16x16x32_bf16 v[134:137], v[162:165], v[170:173], v[134:137]
	v_mfma_f32_16x16x32_bf16 v[118:121], v[162:165], v[178:181], v[118:121]
	v_mfma_f32_16x16x32_bf16 v[122:125], v[154:157], v[178:181], v[122:125]
	v_mfma_f32_16x16x32_bf16 v[106:109], v[154:157], v[186:189], v[106:109]
	v_mfma_f32_16x16x32_bf16 v[102:105], v[162:165], v[186:189], v[102:105]
	v_mfma_f32_16x16x32_bf16 v[70:73], v[162:165], v[194:197], v[70:73]
	v_mfma_f32_16x16x32_bf16 v[74:77], v[154:157], v[194:197], v[74:77]
	s_setprio 0
	s_barrier
	s_add_i32 s61, s61, s49
	v_lshl_add_u64 v[228:229], s[42:43], 0, v[212:213]
	s_mov_b32 m0, s61
	ds_read_b128 v[166:169], v237 offset:16384
	ds_read_b128 v[170:173], v237 offset:17408
	ds_read_b128 v[174:177], v237 offset:18432
	ds_read_b128 v[178:181], v237 offset:19456
	ds_read_b128 v[182:185], v237 offset:20480
	ds_read_b128 v[186:189], v237 offset:21504
	ds_read_b128 v[190:193], v237 offset:22528
	ds_read_b128 v[194:197], v237 offset:23552
	global_load_lds_dwordx4 v[228:229], off
	s_add_i32 m0, s61, 0x2000
	s_add_u32 s62, s42, 0x80000
	v_lshl_add_u64 v[230:231], s[42:43], 0, v[216:217]
	s_addc_u32 s63, s43, 0
	s_add_i32 s61, s64, s49
	global_load_lds_dwordx4 v[230:231], off
	v_lshl_add_u64 v[238:239], s[62:63], 0, v[212:213]
	s_mov_b32 m0, s61
	v_lshl_add_u64 v[240:241], s[44:45], 0, v[214:215]
	global_load_lds_dwordx4 v[238:239], off
	v_lshl_add_u64 v[238:239], s[62:63], 0, v[216:217]
	s_add_i32 m0, s61, 0x2000
	s_nop 0
	global_load_lds_dwordx4 v[238:239], off
	v_lshl_add_u64 v[238:239], s[44:45], 0, v[2:3]
	s_mov_b32 m0, s50
	s_nop 0
	global_load_lds_dwordx4 v[238:239], off
	s_mov_b32 m0, s51
	s_nop 0
	global_load_lds_dwordx4 v[240:241], off
	s_waitcnt vmcnt(8)
	s_waitcnt lgkmcnt(0)
	s_barrier
; #define PG8_STAGE(bufoff, gbase, voff) do { _Pragma("unroll") for (int _i = 0; _i < 2; ++_i) \
;         __builtin_amdgcn_global_load_lds((const unsigned*)((const char*)(gbase) + (voff)[_i]), (LAS unsigned*)(lds + (bufoff) + ldsw + _i * 8192), 16, 0, 0); } while (0)
; #define PG8_LDA(dst, b, h) do { _Pragma("unroll") for (int m = 0; m < 4; ++m) _Pragma("unroll") for (int k = 0; k < 2; ++k) dst[m][k] = *(const LAS bf16x8*)(lds + PG8_SA(b, h) + aoff + m * 2048 + k * 1024); } while (0)
; #define PG8_LDB(dst, b, h) do { _Pragma("unroll") for (int n = 0; n < 2; ++n) _Pragma("unroll") for (int k = 0; k < 2; ++k) dst[n][k] = *(const LAS bf16x8*)(lds + PG8_SB(b, h) + boff + n * 2048 + k * 1024); } while (0)
; #define PG8_MMA(ai, bj, At, Bt) do { __builtin_amdgcn_s_setprio(1); _Pragma("unroll") for (int m = 0; m < 4; ++m) _Pragma("unroll") for (int n = 0; n < 2; ++n) _Pragma("unroll") for (int k = 0; k < 2; ++k) \
;         acc[ai][bj][m][n] = __builtin_amdgcn_mfma_f32_16x16x32_bf16(Bt[n][k], At[m][k], acc[ai][bj][m][n], 0, 0, 0); __builtin_amdgcn_s_setprio(0); } while (0)
; #define PG8_WAIT_V(n) asm volatile("s_waitcnt vmcnt(" #n ")" ::: "memory")
; #define PG8_WAIT_L(n) asm volatile("s_waitcnt lgkmcnt(" #n ")" ::: "memory")
; #define PG8_BAR __builtin_amdgcn_s_barrier()
; #define PG8_SCHED __builtin_amdgcn_sched_barrier(0)
; template <class Epi, class Sched>
; __device__ __forceinline__ void gemm_phase(LAS unsigned char* lds, const Gemm g, const Sched& S, const Epi& E) {
;     ...
;             PG8_WAIT_V(8); PG8_WAIT_L(0); PG8_BAR; PG8_MMA(1, 0, At, B0); PG8_MMA(1, 1, At, B1); PG8_BAR; PG8_SCHED;
;             PG8_LDB(B0, 1, 0); PG8_LDB(B1, 1, 1); PG8_SCHED; PG8_LDA(At, 1, 0); PG8_STAGE(PG8_SA(0, 1), a2 + hstepA, voffA);
;             PG8_WAIT_V(8); PG8_WAIT_L(0); PG8_BAR; PG8_MMA(0, 0, At, B0); PG8_MMA(0, 1, At, B1); PG8_BAR; PG8_SCHED;
	s_setprio 1
	s_waitcnt lgkmcnt(0)
	v_mfma_f32_16x16x32_bf16 v[66:69], v[86:89], v[166:169], v[66:69]
	v_mfma_f32_16x16x32_bf16 v[62:65], v[94:97], v[166:169], v[62:65]
	v_mfma_f32_16x16x32_bf16 v[46:49], v[94:97], v[174:177], v[46:49]
	v_mfma_f32_16x16x32_bf16 v[50:53], v[86:89], v[174:177], v[50:53]
	v_mfma_f32_16x16x32_bf16 v[34:37], v[86:89], v[182:185], v[34:37]
	v_mfma_f32_16x16x32_bf16 v[30:33], v[94:97], v[182:185], v[30:33]
	v_mfma_f32_16x16x32_bf16 v[14:17], v[94:97], v[190:193], v[14:17]
	v_mfma_f32_16x16x32_bf16 v[18:21], v[86:89], v[190:193], v[18:21]
	v_mfma_f32_16x16x32_bf16 v[66:69], v[90:93], v[170:173], v[66:69]
	v_mfma_f32_16x16x32_bf16 v[62:65], v[98:101], v[170:173], v[62:65]
	v_mfma_f32_16x16x32_bf16 v[46:49], v[98:101], v[178:181], v[46:49]
	v_mfma_f32_16x16x32_bf16 v[50:53], v[90:93], v[178:181], v[50:53]
	v_mfma_f32_16x16x32_bf16 v[34:37], v[90:93], v[186:189], v[34:37]
	v_mfma_f32_16x16x32_bf16 v[30:33], v[98:101], v[186:189], v[30:33]
	v_mfma_f32_16x16x32_bf16 v[14:17], v[98:101], v[194:197], v[14:17]
	v_mfma_f32_16x16x32_bf16 v[18:21], v[90:93], v[194:197], v[18:21]
	s_setprio 0
	s_setprio 1
	v_mfma_f32_16x16x32_bf16 v[58:61], v[150:153], v[166:169], v[58:61]
	v_mfma_f32_16x16x32_bf16 v[54:57], v[158:161], v[166:169], v[54:57]
	v_mfma_f32_16x16x32_bf16 v[38:41], v[158:161], v[174:177], v[38:41]
	v_mfma_f32_16x16x32_bf16 v[42:45], v[150:153], v[174:177], v[42:45]
	v_mfma_f32_16x16x32_bf16 v[26:29], v[150:153], v[182:185], v[26:29]
	v_mfma_f32_16x16x32_bf16 v[22:25], v[158:161], v[182:185], v[22:25]
	v_mfma_f32_16x16x32_bf16 v[6:9], v[158:161], v[190:193], v[6:9]
	v_mfma_f32_16x16x32_bf16 v[10:13], v[150:153], v[190:193], v[10:13]
	v_mfma_f32_16x16x32_bf16 v[58:61], v[154:157], v[170:173], v[58:61]
	v_mfma_f32_16x16x32_bf16 v[54:57], v[162:165], v[170:173], v[54:57]
	v_mfma_f32_16x16x32_bf16 v[38:41], v[162:165], v[178:181], v[38:41]
	v_mfma_f32_16x16x32_bf16 v[42:45], v[154:157], v[178:181], v[42:45]
	v_mfma_f32_16x16x32_bf16 v[26:29], v[154:157], v[186:189], v[26:29]
	v_mfma_f32_16x16x32_bf16 v[22:25], v[162:165], v[186:189], v[22:25]
	v_mfma_f32_16x16x32_bf16 v[6:9], v[162:165], v[194:197], v[6:9]
	v_mfma_f32_16x16x32_bf16 v[10:13], v[154:157], v[194:197], v[10:13]
	s_setprio 0
	s_barrier
	s_add_i32 s61, 0, 0x18000
	s_add_i32 s62, 0, 0x1c000
	v_add_u32_e32 v98, s61, v236
	v_add_u32_e32 v162, s62, v236
	ds_read_b128 v[86:89], v98
	ds_read_b128 v[90:93], v98 offset:1024
	ds_read_b128 v[94:97], v98 offset:2048
	ds_read_b128 v[98:101], v98 offset:3072
	ds_read_b128 v[150:153], v162
	ds_read_b128 v[154:157], v162 offset:1024
	ds_read_b128 v[158:161], v162 offset:2048
	ds_read_b128 v[162:165], v162 offset:3072
	s_add_u32 s44, s44, 0x80000
	s_addc_u32 s45, s45, 0
	s_mov_b32 m0, s52
	v_lshl_add_u64 v[242:243], s[44:45], 0, v[2:3]
	ds_read_b128 v[166:169], v237 offset:32768
	ds_read_b128 v[170:173], v237 offset:33792
	ds_read_b128 v[174:177], v237 offset:34816
	ds_read_b128 v[178:181], v237 offset:35840
	ds_read_b128 v[182:185], v237 offset:36864
	ds_read_b128 v[186:189], v237 offset:37888
	ds_read_b128 v[190:193], v237 offset:38912
	ds_read_b128 v[194:197], v237 offset:39936
	global_load_lds_dwordx4 v[242:243], off
	v_lshl_add_u64 v[242:243], s[44:45], 0, v[214:215]
	s_mov_b32 m0, s53
	s_nop 0
	global_load_lds_dwordx4 v[242:243], off
	s_waitcnt vmcnt(8)
	s_waitcnt lgkmcnt(0)
	s_barrier
	s_setprio 1
	s_waitcnt lgkmcnt(0)
	v_mfma_f32_16x16x32_bf16 v[146:149], v[86:89], v[166:169], v[146:149]
	v_mfma_f32_16x16x32_bf16 v[142:145], v[94:97], v[166:169], v[142:145]
	v_mfma_f32_16x16x32_bf16 v[126:129], v[94:97], v[174:177], v[126:129]
	v_mfma_f32_16x16x32_bf16 v[130:133], v[86:89], v[174:177], v[130:133]
	v_mfma_f32_16x16x32_bf16 v[114:117], v[86:89], v[182:185], v[114:117]
	v_mfma_f32_16x16x32_bf16 v[110:113], v[94:97], v[182:185], v[110:113]
	v_mfma_f32_16x16x32_bf16 v[78:81], v[94:97], v[190:193], v[78:81]
	v_mfma_f32_16x16x32_bf16 v[82:85], v[86:89], v[190:193], v[82:85]
	v_mfma_f32_16x16x32_bf16 v[146:149], v[90:93], v[170:173], v[146:149]
	v_mfma_f32_16x16x32_bf16 v[142:145], v[98:101], v[170:173], v[142:145]
	v_mfma_f32_16x16x32_bf16 v[126:129], v[98:101], v[178:181], v[126:129]
	v_mfma_f32_16x16x32_bf16 v[130:133], v[90:93], v[178:181], v[130:133]
	v_mfma_f32_16x16x32_bf16 v[114:117], v[90:93], v[186:189], v[114:117]
	v_mfma_f32_16x16x32_bf16 v[110:113], v[98:101], v[186:189], v[110:113]
	v_mfma_f32_16x16x32_bf16 v[78:81], v[98:101], v[194:197], v[78:81]
	v_mfma_f32_16x16x32_bf16 v[82:85], v[90:93], v[194:197], v[82:85]
	s_setprio 0
	s_setprio 1
	v_mfma_f32_16x16x32_bf16 v[138:141], v[150:153], v[166:169], v[138:141]
	v_mfma_f32_16x16x32_bf16 v[134:137], v[158:161], v[166:169], v[134:137]
	v_mfma_f32_16x16x32_bf16 v[118:121], v[158:161], v[174:177], v[118:121]
	v_mfma_f32_16x16x32_bf16 v[122:125], v[150:153], v[174:177], v[122:125]
	v_mfma_f32_16x16x32_bf16 v[106:109], v[150:153], v[182:185], v[106:109]
	v_mfma_f32_16x16x32_bf16 v[102:105], v[158:161], v[182:185], v[102:105]
	v_mfma_f32_16x16x32_bf16 v[70:73], v[158:161], v[190:193], v[70:73]
	v_mfma_f32_16x16x32_bf16 v[74:77], v[150:153], v[190:193], v[74:77]
	v_mfma_f32_16x16x32_bf16 v[138:141], v[154:157], v[170:173], v[138:141]
	v_mfma_f32_16x16x32_bf16 v[134:137], v[162:165], v[170:173], v[134:137]
	v_mfma_f32_16x16x32_bf16 v[118:121], v[162:165], v[178:181], v[118:121]
	v_mfma_f32_16x16x32_bf16 v[122:125], v[154:157], v[178:181], v[122:125]
	v_mfma_f32_16x16x32_bf16 v[106:109], v[154:157], v[186:189], v[106:109]
	v_mfma_f32_16x16x32_bf16 v[102:105], v[162:165], v[186:189], v[102:105]
	v_mfma_f32_16x16x32_bf16 v[70:73], v[162:165], v[194:197], v[70:73]
	v_mfma_f32_16x16x32_bf16 v[74:77], v[154:157], v[194:197], v[74:77]
	s_setprio 0
	s_barrier
; #define PG8_STAGE(bufoff, gbase, voff) do { _Pragma("unroll") for (int _i = 0; _i < 2; ++_i) \
;         __builtin_amdgcn_global_load_lds((const unsigned*)((const char*)(gbase) + (voff)[_i]), (LAS unsigned*)(lds + (bufoff) + ldsw + _i * 8192), 16, 0, 0); } while (0)
; #define PG8_LDA(dst, b, h) do { _Pragma("unroll") for (int m = 0; m < 4; ++m) _Pragma("unroll") for (int k = 0; k < 2; ++k) dst[m][k] = *(const LAS bf16x8*)(lds + PG8_SA(b, h) + aoff + m * 2048 + k * 1024); } while (0)
; #define PG8_MMA(ai, bj, At, Bt) do { __builtin_amdgcn_s_setprio(1); _Pragma("unroll") for (int m = 0; m < 4; ++m) _Pragma("unroll") for (int n = 0; n < 2; ++n) _Pragma("unroll") for (int k = 0; k < 2; ++k) \
;         acc[ai][bj][m][n] = __builtin_amdgcn_mfma_f32_16x16x32_bf16(Bt[n][k], At[m][k], acc[ai][bj][m][n], 0, 0, 0); __builtin_amdgcn_s_setprio(0); } while (0)
; #define PG8_WAIT_V(n) asm volatile("s_waitcnt vmcnt(" #n ")" ::: "memory")
; #define PG8_WAIT_L(n) asm volatile("s_waitcnt lgkmcnt(" #n ")" ::: "memory")
; #define PG8_BAR __builtin_amdgcn_s_barrier()
; #define PG8_SCHED __builtin_amdgcn_sched_barrier(0)
; template <class Epi, class Sched>
; __device__ __forceinline__ void gemm_phase(LAS unsigned char* lds, const Gemm g, const Sched& S, const Epi& E) {
;     ...
;         for (int t = 0; t < nt; t += 2) {
;     ...
;             PG8_LDA(At, 1, 1); PG8_STAGE(PG8_SB(1, 0), b3, voffB); PG8_STAGE(PG8_SB(1, 1), b3 + hstepB, voffB); PG8_STAGE(PG8_SA(1, 0), a3, voffA);
;             PG8_WAIT_V(8); PG8_WAIT_L(0); PG8_BAR; PG8_MMA(1, 0, At, B0); PG8_MMA(1, 1, At, B1); PG8_BAR; PG8_SCHED;
;         }
	s_add_i32 s44, s61, s49
	v_lshl_add_u64 v[228:229], v[228:229], 0, s[36:37]
	s_mov_b32 m0, s44
	ds_read_b128 v[166:169], v237 offset:49152
	ds_read_b128 v[170:173], v237 offset:50176
	ds_read_b128 v[174:177], v237 offset:51200
	ds_read_b128 v[178:181], v237 offset:52224
	ds_read_b128 v[182:185], v237 offset:53248
	ds_read_b128 v[186:189], v237 offset:54272
	ds_read_b128 v[190:193], v237 offset:55296
	ds_read_b128 v[194:197], v237 offset:56320
	global_load_lds_dwordx4 v[228:229], off
	s_add_i32 m0, s44, 0x2000
	s_add_u32 s42, s42, 0x80080
	v_lshl_add_u64 v[228:229], v[230:231], 0, s[36:37]
	s_addc_u32 s43, s43, 0
	s_add_i32 s44, s62, s49
	global_load_lds_dwordx4 v[228:229], off
	v_lshl_add_u64 v[228:229], s[42:43], 0, v[212:213]
	s_mov_b32 m0, s44
	s_nop 0
	global_load_lds_dwordx4 v[228:229], off
	v_lshl_add_u64 v[228:229], s[42:43], 0, v[216:217]
	s_add_i32 m0, s44, 0x2000
	s_nop 0
	global_load_lds_dwordx4 v[228:229], off
	v_lshl_add_u64 v[228:229], v[238:239], 0, s[36:37]
	s_mov_b32 m0, s54
	s_nop 0
	global_load_lds_dwordx4 v[228:229], off
	v_lshl_add_u64 v[228:229], v[240:241], 0, s[36:37]
	s_mov_b32 m0, s55
	s_nop 0
	global_load_lds_dwordx4 v[228:229], off
	s_waitcnt vmcnt(8)
	s_waitcnt lgkmcnt(0)
	s_barrier
	s_setprio 1
	s_waitcnt lgkmcnt(0)
	v_mfma_f32_16x16x32_bf16 v[66:69], v[86:89], v[166:169], v[66:69]
	v_mfma_f32_16x16x32_bf16 v[62:65], v[94:97], v[166:169], v[62:65]
	v_mfma_f32_16x16x32_bf16 v[46:49], v[94:97], v[174:177], v[46:49]
	v_mfma_f32_16x16x32_bf16 v[50:53], v[86:89], v[174:177], v[50:53]
	v_mfma_f32_16x16x32_bf16 v[34:37], v[86:89], v[182:185], v[34:37]
	v_mfma_f32_16x16x32_bf16 v[30:33], v[94:97], v[182:185], v[30:33]
	v_mfma_f32_16x16x32_bf16 v[14:17], v[94:97], v[190:193], v[14:17]
	v_mfma_f32_16x16x32_bf16 v[18:21], v[86:89], v[190:193], v[18:21]
	v_mfma_f32_16x16x32_bf16 v[66:69], v[90:93], v[170:173], v[66:69]
	v_mfma_f32_16x16x32_bf16 v[62:65], v[98:101], v[170:173], v[62:65]
	v_mfma_f32_16x16x32_bf16 v[46:49], v[98:101], v[178:181], v[46:49]
	v_mfma_f32_16x16x32_bf16 v[50:53], v[90:93], v[178:181], v[50:53]
	v_mfma_f32_16x16x32_bf16 v[34:37], v[90:93], v[186:189], v[34:37]
	v_mfma_f32_16x16x32_bf16 v[30:33], v[98:101], v[186:189], v[30:33]
	v_mfma_f32_16x16x32_bf16 v[14:17], v[98:101], v[194:197], v[14:17]
	v_mfma_f32_16x16x32_bf16 v[18:21], v[90:93], v[194:197], v[18:21]
	s_setprio 0
	s_setprio 1
	v_mfma_f32_16x16x32_bf16 v[58:61], v[150:153], v[166:169], v[58:61]
	v_mfma_f32_16x16x32_bf16 v[54:57], v[158:161], v[166:169], v[54:57]
	v_mfma_f32_16x16x32_bf16 v[38:41], v[158:161], v[174:177], v[38:41]
	v_mfma_f32_16x16x32_bf16 v[42:45], v[150:153], v[174:177], v[42:45]
	v_mfma_f32_16x16x32_bf16 v[26:29], v[150:153], v[182:185], v[26:29]
	v_mfma_f32_16x16x32_bf16 v[22:25], v[158:161], v[182:185], v[22:25]
	v_mfma_f32_16x16x32_bf16 v[6:9], v[158:161], v[190:193], v[6:9]
	v_mfma_f32_16x16x32_bf16 v[10:13], v[150:153], v[190:193], v[10:13]
	v_mfma_f32_16x16x32_bf16 v[58:61], v[154:157], v[170:173], v[58:61]
	v_mfma_f32_16x16x32_bf16 v[54:57], v[162:165], v[170:173], v[54:57]
	v_mfma_f32_16x16x32_bf16 v[38:41], v[162:165], v[178:181], v[38:41]
	v_mfma_f32_16x16x32_bf16 v[42:45], v[154:157], v[178:181], v[42:45]
	v_mfma_f32_16x16x32_bf16 v[26:29], v[154:157], v[186:189], v[26:29]
	v_mfma_f32_16x16x32_bf16 v[22:25], v[162:165], v[186:189], v[22:25]
	v_mfma_f32_16x16x32_bf16 v[6:9], v[162:165], v[194:197], v[6:9]
	v_mfma_f32_16x16x32_bf16 v[10:13], v[154:157], v[194:197], v[10:13]
	s_setprio 0
	s_barrier
	s_add_i32 s60, s60, 2
	s_add_u32 s38, s38, 0x100
	s_addc_u32 s39, s39, 0
	s_add_u32 s58, s58, 0x100
	s_addc_u32 s59, s59, 0
	s_cmp_gt_u32 s60, 29
	s_cbranch_scc0 .LBB0_513
	s_and_b64 vcc, exec, s[16:17]
	s_cbranch_vccz .LBB0_516
	s_barrier

; #define PG8_STAGE(bufoff, gbase, voff) do { _Pragma("unroll") for (int _i = 0; _i < 2; ++_i) \
;         __builtin_amdgcn_global_load_lds((const unsigned*)((const char*)(gbase) + (voff)[_i]), (LAS unsigned*)(lds + (bufoff) + ldsw + _i * 8192), 16, 0, 0); } while (0)
; #define PG8_LDA(dst, b, h) do { _Pragma("unroll") for (int m = 0; m < 4; ++m) _Pragma("unroll") for (int k = 0; k < 2; ++k) dst[m][k] = *(const LAS bf16x8*)(lds + PG8_SA(b, h) + aoff + m * 2048 + k * 1024); } while (0)
; #define PG8_LDB(dst, b, h) do { _Pragma("unroll") for (int n = 0; n < 2; ++n) _Pragma("unroll") for (int k = 0; k < 2; ++k) dst[n][k] = *(const LAS bf16x8*)(lds + PG8_SB(b, h) + boff + n * 2048 + k * 1024); } while (0)
; #define PG8_MMA(ai, bj, At, Bt) do { __builtin_amdgcn_s_setprio(1); _Pragma("unroll") for (int m = 0; m < 4; ++m) _Pragma("unroll") for (int n = 0; n < 2; ++n) _Pragma("unroll") for (int k = 0; k < 2; ++k) \
;         acc[ai][bj][m][n] = __builtin_amdgcn_mfma_f32_16x16x32_bf16(Bt[n][k], At[m][k], acc[ai][bj][m][n], 0, 0, 0); __builtin_amdgcn_s_setprio(0); } while (0)
; #define PG8_WAIT_V(n) asm volatile("s_waitcnt vmcnt(" #n ")" ::: "memory")
; #define PG8_WAIT_L(n) asm volatile("s_waitcnt lgkmcnt(" #n ")" ::: "memory")
; #define PG8_BAR __builtin_amdgcn_s_barrier()
; #define PG8_SCHED __builtin_amdgcn_sched_barrier(0)
; template <class Epi, class Sched>
; __device__ __forceinline__ void gemm_phase(LAS unsigned char* lds, const Gemm g, const Sched& S, const Epi& E) {
;     ...
;             PG8_LDB(B0, 0, 0); PG8_LDB(B1, 0, 1); PG8_SCHED; PG8_LDA(At, 0, 0); PG8_STAGE(PG8_SA(1, 1), a1 + hstepA, voffA);
;             PG8_WAIT_V(8); PG8_WAIT_L(0); PG8_BAR; PG8_MMA(0, 0, At, B0); PG8_MMA(0, 1, At, B1); PG8_BAR; PG8_SCHED;
;             PG8_LDA(At, 0, 1); PG8_STAGE(PG8_SB(0, 0), b2, voffB); PG8_STAGE(PG8_SB(0, 1), b2 + hstepB, voffB); PG8_STAGE(PG8_SA(0, 0), a2, voffA);
.LBB0_655:
	s_add_u32 s28, s26, 0xfff80080
	s_addc_u32 s29, s27, -1
	s_add_i32 s57, 0, 0x10000
	s_cmp_eq_u32 s56, 28
	s_cselect_b32 s41, s17, s29
	s_cselect_b32 s40, s23, s28
	v_add_u32_e32 v4, s57, v231
	s_cselect_b32 s29, s15, s55
	s_cselect_b32 s28, s25, s34
	s_add_i32 s60, 0, 0x14000
	ds_read_b128 v[134:137], v4
	ds_read_b128 v[138:141], v4 offset:1024
	ds_read_b128 v[142:145], v4 offset:2048
	ds_read_b128 v[146:149], v4 offset:3072
	v_add_u32_e32 v4, s60, v231
	ds_read_b128 v[150:153], v4
	ds_read_b128 v[154:157], v4 offset:1024
	ds_read_b128 v[158:161], v4 offset:2048
	ds_read_b128 v[162:165], v4 offset:3072
	v_lshl_add_u64 v[236:237], s[26:27], 0, v[196:197]
	s_add_i32 m0, s47, 0xc000
	ds_read_b128 v[166:169], v235
	ds_read_b128 v[170:173], v235 offset:1024
	ds_read_b128 v[174:177], v235 offset:2048
	ds_read_b128 v[178:181], v235 offset:3072
	ds_read_b128 v[214:217], v235 offset:4096
	ds_read_b128 v[218:221], v235 offset:5120
	ds_read_b128 v[222:225], v235 offset:6144
	ds_read_b128 v[226:229], v235 offset:7168
	global_load_lds_dwordx4 v[236:237], off
	v_lshl_add_u64 v[236:237], s[26:27], 0, v[212:213]
	s_add_i32 m0, s47, 0xe000
	s_nop 0
	global_load_lds_dwordx4 v[236:237], off
	s_waitcnt vmcnt(8)
	s_waitcnt lgkmcnt(0)
	s_barrier
	s_setprio 1
	s_waitcnt lgkmcnt(0)
	v_mfma_f32_16x16x32_bf16 v[130:133], v[134:137], v[166:169], v[130:133]
	v_mfma_f32_16x16x32_bf16 v[126:129], v[142:145], v[166:169], v[126:129]
	v_mfma_f32_16x16x32_bf16 v[110:113], v[142:145], v[174:177], v[110:113]
	v_mfma_f32_16x16x32_bf16 v[114:117], v[134:137], v[174:177], v[114:117]
	v_mfma_f32_16x16x32_bf16 v[98:101], v[134:137], v[214:217], v[98:101]
	v_mfma_f32_16x16x32_bf16 v[94:97], v[142:145], v[214:217], v[94:97]
	v_mfma_f32_16x16x32_bf16 v[78:81], v[142:145], v[222:225], v[78:81]
	v_mfma_f32_16x16x32_bf16 v[82:85], v[134:137], v[222:225], v[82:85]
	v_mfma_f32_16x16x32_bf16 v[130:133], v[138:141], v[170:173], v[130:133]
	v_mfma_f32_16x16x32_bf16 v[126:129], v[146:149], v[170:173], v[126:129]
	v_mfma_f32_16x16x32_bf16 v[110:113], v[146:149], v[178:181], v[110:113]
	v_mfma_f32_16x16x32_bf16 v[114:117], v[138:141], v[178:181], v[114:117]
	v_mfma_f32_16x16x32_bf16 v[98:101], v[138:141], v[218:221], v[98:101]
	v_mfma_f32_16x16x32_bf16 v[94:97], v[146:149], v[218:221], v[94:97]
	v_mfma_f32_16x16x32_bf16 v[78:81], v[146:149], v[226:229], v[78:81]
	v_mfma_f32_16x16x32_bf16 v[82:85], v[138:141], v[226:229], v[82:85]
	s_setprio 0
	s_setprio 1
	v_mfma_f32_16x16x32_bf16 v[122:125], v[150:153], v[166:169], v[122:125]
	v_mfma_f32_16x16x32_bf16 v[118:121], v[158:161], v[166:169], v[118:121]
	v_mfma_f32_16x16x32_bf16 v[102:105], v[158:161], v[174:177], v[102:105]
	v_mfma_f32_16x16x32_bf16 v[106:109], v[150:153], v[174:177], v[106:109]
	v_mfma_f32_16x16x32_bf16 v[90:93], v[150:153], v[214:217], v[90:93]
	v_mfma_f32_16x16x32_bf16 v[86:89], v[158:161], v[214:217], v[86:89]
	v_mfma_f32_16x16x32_bf16 v[70:73], v[158:161], v[222:225], v[70:73]
	v_mfma_f32_16x16x32_bf16 v[74:77], v[150:153], v[222:225], v[74:77]
	v_mfma_f32_16x16x32_bf16 v[122:125], v[154:157], v[170:173], v[122:125]
	v_mfma_f32_16x16x32_bf16 v[118:121], v[162:165], v[170:173], v[118:121]
	v_mfma_f32_16x16x32_bf16 v[102:105], v[162:165], v[178:181], v[102:105]
	v_mfma_f32_16x16x32_bf16 v[106:109], v[154:157], v[178:181], v[106:109]
	v_mfma_f32_16x16x32_bf16 v[90:93], v[154:157], v[218:221], v[90:93]
	v_mfma_f32_16x16x32_bf16 v[86:89], v[162:165], v[218:221], v[86:89]
	v_mfma_f32_16x16x32_bf16 v[70:73], v[162:165], v[226:229], v[70:73]
	v_mfma_f32_16x16x32_bf16 v[74:77], v[154:157], v[226:229], v[74:77]
	s_setprio 0
	s_barrier
	s_add_i32 s57, s57, s46
	v_lshl_add_u64 v[236:237], s[28:29], 0, v[182:183]
	s_mov_b32 m0, s57
	ds_read_b128 v[166:169], v235 offset:16384
	ds_read_b128 v[170:173], v235 offset:17408
	ds_read_b128 v[174:177], v235 offset:18432
	ds_read_b128 v[178:181], v235 offset:19456
	ds_read_b128 v[214:217], v235 offset:20480
	ds_read_b128 v[218:221], v235 offset:21504
	ds_read_b128 v[222:225], v235 offset:22528
	ds_read_b128 v[226:229], v235 offset:23552
	global_load_lds_dwordx4 v[236:237], off
	s_add_i32 m0, s57, 0x2000
	s_add_u32 s58, s28, 0x80000
	v_lshl_add_u64 v[238:239], s[28:29], 0, v[186:187]
	s_addc_u32 s59, s29, 0
	s_add_i32 s57, s60, s46
	global_load_lds_dwordx4 v[238:239], off
	v_lshl_add_u64 v[240:241], s[58:59], 0, v[182:183]
	s_mov_b32 m0, s57
	v_lshl_add_u64 v[242:243], s[40:41], 0, v[184:185]
	global_load_lds_dwordx4 v[240:241], off
	v_lshl_add_u64 v[240:241], s[58:59], 0, v[186:187]
	s_add_i32 m0, s57, 0x2000
	s_nop 0
	global_load_lds_dwordx4 v[240:241], off
	v_lshl_add_u64 v[240:241], s[40:41], 0, v[2:3]
	s_mov_b32 m0, s47
	s_nop 0
	global_load_lds_dwordx4 v[240:241], off
	s_mov_b32 m0, s48
	s_nop 0
	global_load_lds_dwordx4 v[242:243], off
	s_waitcnt vmcnt(8)
	s_waitcnt lgkmcnt(0)
	s_barrier
; #define PG8_STAGE(bufoff, gbase, voff) do { _Pragma("unroll") for (int _i = 0; _i < 2; ++_i) \
;         __builtin_amdgcn_global_load_lds((const unsigned*)((const char*)(gbase) + (voff)[_i]), (LAS unsigned*)(lds + (bufoff) + ldsw + _i * 8192), 16, 0, 0); } while (0)
; #define PG8_LDA(dst, b, h) do { _Pragma("unroll") for (int m = 0; m < 4; ++m) _Pragma("unroll") for (int k = 0; k < 2; ++k) dst[m][k] = *(const LAS bf16x8*)(lds + PG8_SA(b, h) + aoff + m * 2048 + k * 1024); } while (0)
; #define PG8_LDB(dst, b, h) do { _Pragma("unroll") for (int n = 0; n < 2; ++n) _Pragma("unroll") for (int k = 0; k < 2; ++k) dst[n][k] = *(const LAS bf16x8*)(lds + PG8_SB(b, h) + boff + n * 2048 + k * 1024); } while (0)
; #define PG8_MMA(ai, bj, At, Bt) do { __builtin_amdgcn_s_setprio(1); _Pragma("unroll") for (int m = 0; m < 4; ++m) _Pragma("unroll") for (int n = 0; n < 2; ++n) _Pragma("unroll") for (int k = 0; k < 2; ++k) \
;         acc[ai][bj][m][n] = __builtin_amdgcn_mfma_f32_16x16x32_bf16(Bt[n][k], At[m][k], acc[ai][bj][m][n], 0, 0, 0); __builtin_amdgcn_s_setprio(0); } while (0)
; #define PG8_WAIT_V(n) asm volatile("s_waitcnt vmcnt(" #n ")" ::: "memory")
; #define PG8_WAIT_L(n) asm volatile("s_waitcnt lgkmcnt(" #n ")" ::: "memory")
; #define PG8_BAR __builtin_amdgcn_s_barrier()
; #define PG8_SCHED __builtin_amdgcn_sched_barrier(0)
; template <class Epi, class Sched>
; __device__ __forceinline__ void gemm_phase(LAS unsigned char* lds, const Gemm g, const Sched& S, const Epi& E) {
;     ...
;             PG8_WAIT_V(8); PG8_WAIT_L(0); PG8_BAR; PG8_MMA(1, 0, At, B0); PG8_MMA(1, 1, At, B1); PG8_BAR; PG8_SCHED;
;             PG8_LDB(B0, 1, 0); PG8_LDB(B1, 1, 1); PG8_SCHED; PG8_LDA(At, 1, 0); PG8_STAGE(PG8_SA(0, 1), a2 + hstepA, voffA);
;             PG8_WAIT_V(8); PG8_WAIT_L(0); PG8_BAR; PG8_MMA(0, 0, At, B0); PG8_MMA(0, 1, At, B1); PG8_BAR; PG8_SCHED;
	s_setprio 1
	s_waitcnt lgkmcnt(0)
	v_mfma_f32_16x16x32_bf16 v[66:69], v[134:137], v[166:169], v[66:69]
	v_mfma_f32_16x16x32_bf16 v[62:65], v[142:145], v[166:169], v[62:65]
	v_mfma_f32_16x16x32_bf16 v[46:49], v[142:145], v[174:177], v[46:49]
	v_mfma_f32_16x16x32_bf16 v[50:53], v[134:137], v[174:177], v[50:53]
	v_mfma_f32_16x16x32_bf16 v[34:37], v[134:137], v[214:217], v[34:37]
	v_mfma_f32_16x16x32_bf16 v[30:33], v[142:145], v[214:217], v[30:33]
	v_mfma_f32_16x16x32_bf16 v[14:17], v[142:145], v[222:225], v[14:17]
	v_mfma_f32_16x16x32_bf16 v[18:21], v[134:137], v[222:225], v[18:21]
	v_mfma_f32_16x16x32_bf16 v[66:69], v[138:141], v[170:173], v[66:69]
	v_mfma_f32_16x16x32_bf16 v[62:65], v[146:149], v[170:173], v[62:65]
	v_mfma_f32_16x16x32_bf16 v[46:49], v[146:149], v[178:181], v[46:49]
	v_mfma_f32_16x16x32_bf16 v[50:53], v[138:141], v[178:181], v[50:53]
	v_mfma_f32_16x16x32_bf16 v[34:37], v[138:141], v[218:221], v[34:37]
	v_mfma_f32_16x16x32_bf16 v[30:33], v[146:149], v[218:221], v[30:33]
	v_mfma_f32_16x16x32_bf16 v[14:17], v[146:149], v[226:229], v[14:17]
	v_mfma_f32_16x16x32_bf16 v[18:21], v[138:141], v[226:229], v[18:21]
	s_setprio 0
	s_setprio 1
	v_mfma_f32_16x16x32_bf16 v[58:61], v[150:153], v[166:169], v[58:61]
	v_mfma_f32_16x16x32_bf16 v[54:57], v[158:161], v[166:169], v[54:57]
	v_mfma_f32_16x16x32_bf16 v[38:41], v[158:161], v[174:177], v[38:41]
	v_mfma_f32_16x16x32_bf16 v[42:45], v[150:153], v[174:177], v[42:45]
	v_mfma_f32_16x16x32_bf16 v[26:29], v[150:153], v[214:217], v[26:29]
	v_mfma_f32_16x16x32_bf16 v[22:25], v[158:161], v[214:217], v[22:25]
	v_mfma_f32_16x16x32_bf16 v[6:9], v[158:161], v[222:225], v[6:9]
	v_mfma_f32_16x16x32_bf16 v[10:13], v[150:153], v[222:225], v[10:13]
	v_mfma_f32_16x16x32_bf16 v[58:61], v[154:157], v[170:173], v[58:61]
	v_mfma_f32_16x16x32_bf16 v[54:57], v[162:165], v[170:173], v[54:57]
	v_mfma_f32_16x16x32_bf16 v[38:41], v[162:165], v[178:181], v[38:41]
	v_mfma_f32_16x16x32_bf16 v[42:45], v[154:157], v[178:181], v[42:45]
	v_mfma_f32_16x16x32_bf16 v[26:29], v[154:157], v[218:221], v[26:29]
	v_mfma_f32_16x16x32_bf16 v[22:25], v[162:165], v[218:221], v[22:25]
	v_mfma_f32_16x16x32_bf16 v[6:9], v[162:165], v[226:229], v[6:9]
	v_mfma_f32_16x16x32_bf16 v[10:13], v[154:157], v[226:229], v[10:13]
	s_setprio 0
	s_barrier
	s_add_i32 s57, 0, 0x18000
	v_add_u32_e32 v4, s57, v231
	s_add_i32 s58, 0, 0x1c000
	ds_read_b128 v[134:137], v4
	ds_read_b128 v[138:141], v4 offset:1024
	ds_read_b128 v[142:145], v4 offset:2048
	ds_read_b128 v[146:149], v4 offset:3072
	v_add_u32_e32 v4, s58, v231
	ds_read_b128 v[150:153], v4
	ds_read_b128 v[154:157], v4 offset:1024
	ds_read_b128 v[158:161], v4 offset:2048
	ds_read_b128 v[162:165], v4 offset:3072
	s_add_u32 s40, s40, 0x80000
	s_addc_u32 s41, s41, 0
	s_mov_b32 m0, s49
	v_lshl_add_u64 v[244:245], s[40:41], 0, v[2:3]
	ds_read_b128 v[166:169], v235 offset:32768
	ds_read_b128 v[170:173], v235 offset:33792
	ds_read_b128 v[174:177], v235 offset:34816
	ds_read_b128 v[178:181], v235 offset:35840
	ds_read_b128 v[214:217], v235 offset:36864
	ds_read_b128 v[218:221], v235 offset:37888
	ds_read_b128 v[222:225], v235 offset:38912
	ds_read_b128 v[226:229], v235 offset:39936
	global_load_lds_dwordx4 v[244:245], off
	v_lshl_add_u64 v[244:245], s[40:41], 0, v[184:185]
	s_mov_b32 m0, s50
	s_nop 0
	global_load_lds_dwordx4 v[244:245], off
	s_waitcnt vmcnt(8)
	s_waitcnt lgkmcnt(0)
	s_barrier
	s_setprio 1
	s_waitcnt lgkmcnt(0)
	v_mfma_f32_16x16x32_bf16 v[130:133], v[134:137], v[166:169], v[130:133]
	v_mfma_f32_16x16x32_bf16 v[126:129], v[142:145], v[166:169], v[126:129]
	v_mfma_f32_16x16x32_bf16 v[110:113], v[142:145], v[174:177], v[110:113]
	v_mfma_f32_16x16x32_bf16 v[114:117], v[134:137], v[174:177], v[114:117]
	v_mfma_f32_16x16x32_bf16 v[98:101], v[134:137], v[214:217], v[98:101]
	v_mfma_f32_16x16x32_bf16 v[94:97], v[142:145], v[214:217], v[94:97]
	v_mfma_f32_16x16x32_bf16 v[78:81], v[142:145], v[222:225], v[78:81]
	v_mfma_f32_16x16x32_bf16 v[82:85], v[134:137], v[222:225], v[82:85]
	v_mfma_f32_16x16x32_bf16 v[130:133], v[138:141], v[170:173], v[130:133]
	v_mfma_f32_16x16x32_bf16 v[126:129], v[146:149], v[170:173], v[126:129]
	v_mfma_f32_16x16x32_bf16 v[110:113], v[146:149], v[178:181], v[110:113]
	v_mfma_f32_16x16x32_bf16 v[114:117], v[138:141], v[178:181], v[114:117]
	v_mfma_f32_16x16x32_bf16 v[98:101], v[138:141], v[218:221], v[98:101]
	v_mfma_f32_16x16x32_bf16 v[94:97], v[146:149], v[218:221], v[94:97]
	v_mfma_f32_16x16x32_bf16 v[78:81], v[146:149], v[226:229], v[78:81]
	v_mfma_f32_16x16x32_bf16 v[82:85], v[138:141], v[226:229], v[82:85]
	s_setprio 0
	s_setprio 1
	v_mfma_f32_16x16x32_bf16 v[122:125], v[150:153], v[166:169], v[122:125]
	v_mfma_f32_16x16x32_bf16 v[118:121], v[158:161], v[166:169], v[118:121]
	v_mfma_f32_16x16x32_bf16 v[102:105], v[158:161], v[174:177], v[102:105]
	v_mfma_f32_16x16x32_bf16 v[106:109], v[150:153], v[174:177], v[106:109]
	v_mfma_f32_16x16x32_bf16 v[90:93], v[150:153], v[214:217], v[90:93]
	v_mfma_f32_16x16x32_bf16 v[86:89], v[158:161], v[214:217], v[86:89]
	v_mfma_f32_16x16x32_bf16 v[70:73], v[158:161], v[222:225], v[70:73]
	v_mfma_f32_16x16x32_bf16 v[74:77], v[150:153], v[222:225], v[74:77]
	v_mfma_f32_16x16x32_bf16 v[122:125], v[154:157], v[170:173], v[122:125]
	v_mfma_f32_16x16x32_bf16 v[118:121], v[162:165], v[170:173], v[118:121]
	v_mfma_f32_16x16x32_bf16 v[102:105], v[162:165], v[178:181], v[102:105]
	v_mfma_f32_16x16x32_bf16 v[106:109], v[154:157], v[178:181], v[106:109]
	v_mfma_f32_16x16x32_bf16 v[90:93], v[154:157], v[218:221], v[90:93]
	v_mfma_f32_16x16x32_bf16 v[86:89], v[162:165], v[218:221], v[86:89]
	v_mfma_f32_16x16x32_bf16 v[70:73], v[162:165], v[226:229], v[70:73]
	v_mfma_f32_16x16x32_bf16 v[74:77], v[154:157], v[226:229], v[74:77]
	s_setprio 0
	s_barrier
; #define PG8_STAGE(bufoff, gbase, voff) do { _Pragma("unroll") for (int _i = 0; _i < 2; ++_i) \
;         __builtin_amdgcn_global_load_lds((const unsigned*)((const char*)(gbase) + (voff)[_i]), (LAS unsigned*)(lds + (bufoff) + ldsw + _i * 8192), 16, 0, 0); } while (0)
; #define PG8_LDA(dst, b, h) do { _Pragma("unroll") for (int m = 0; m < 4; ++m) _Pragma("unroll") for (int k = 0; k < 2; ++k) dst[m][k] = *(const LAS bf16x8*)(lds + PG8_SA(b, h) + aoff + m * 2048 + k * 1024); } while (0)
; #define PG8_MMA(ai, bj, At, Bt) do { __builtin_amdgcn_s_setprio(1); _Pragma("unroll") for (int m = 0; m < 4; ++m) _Pragma("unroll") for (int n = 0; n < 2; ++n) _Pragma("unroll") for (int k = 0; k < 2; ++k) \
;         acc[ai][bj][m][n] = __builtin_amdgcn_mfma_f32_16x16x32_bf16(Bt[n][k], At[m][k], acc[ai][bj][m][n], 0, 0, 0); __builtin_amdgcn_s_setprio(0); } while (0)
; #define PG8_WAIT_V(n) asm volatile("s_waitcnt vmcnt(" #n ")" ::: "memory")
; #define PG8_WAIT_L(n) asm volatile("s_waitcnt lgkmcnt(" #n ")" ::: "memory")
; #define PG8_BAR __builtin_amdgcn_s_barrier()
; #define PG8_SCHED __builtin_amdgcn_sched_barrier(0)
; template <class Epi, class Sched>
; __device__ __forceinline__ void gemm_phase(LAS unsigned char* lds, const Gemm g, const Sched& S, const Epi& E) {
;     ...
;         for (int t = 0; t < nt; t += 2) {
;     ...
;             PG8_LDA(At, 1, 1); PG8_STAGE(PG8_SB(1, 0), b3, voffB); PG8_STAGE(PG8_SB(1, 1), b3 + hstepB, voffB); PG8_STAGE(PG8_SA(1, 0), a3, voffA);
;             PG8_WAIT_V(8); PG8_WAIT_L(0); PG8_BAR; PG8_MMA(1, 0, At, B0); PG8_MMA(1, 1, At, B1); PG8_BAR; PG8_SCHED;
;         }
	s_add_i32 s40, s57, s46
	v_lshl_add_u64 v[236:237], v[236:237], 0, s[36:37]
	s_mov_b32 m0, s40
	ds_read_b128 v[166:169], v235 offset:49152
	ds_read_b128 v[170:173], v235 offset:50176
	ds_read_b128 v[174:177], v235 offset:51200
	ds_read_b128 v[178:181], v235 offset:52224
	ds_read_b128 v[214:217], v235 offset:53248
	ds_read_b128 v[218:221], v235 offset:54272
	ds_read_b128 v[222:225], v235 offset:55296
	ds_read_b128 v[226:229], v235 offset:56320
	global_load_lds_dwordx4 v[236:237], off
	s_add_i32 m0, s40, 0x2000
	s_add_u32 s28, s28, 0x80080
	v_lshl_add_u64 v[236:237], v[238:239], 0, s[36:37]
	s_addc_u32 s29, s29, 0
	s_add_i32 s40, s58, s46
	global_load_lds_dwordx4 v[236:237], off
	v_lshl_add_u64 v[236:237], s[28:29], 0, v[182:183]
	s_mov_b32 m0, s40
	s_nop 0
	global_load_lds_dwordx4 v[236:237], off
	v_lshl_add_u64 v[236:237], s[28:29], 0, v[186:187]
	s_add_i32 m0, s40, 0x2000
	s_nop 0
	global_load_lds_dwordx4 v[236:237], off
	v_lshl_add_u64 v[236:237], v[240:241], 0, s[36:37]
	s_mov_b32 m0, s52
	s_nop 0
	global_load_lds_dwordx4 v[236:237], off
	v_lshl_add_u64 v[236:237], v[242:243], 0, s[36:37]
	s_mov_b32 m0, s53
	s_nop 0
	global_load_lds_dwordx4 v[236:237], off
	s_waitcnt vmcnt(8)
	s_waitcnt lgkmcnt(0)
	s_barrier
	s_setprio 1
	s_waitcnt lgkmcnt(0)
	v_mfma_f32_16x16x32_bf16 v[66:69], v[134:137], v[166:169], v[66:69]
	v_mfma_f32_16x16x32_bf16 v[62:65], v[142:145], v[166:169], v[62:65]
	v_mfma_f32_16x16x32_bf16 v[46:49], v[142:145], v[174:177], v[46:49]
	v_mfma_f32_16x16x32_bf16 v[50:53], v[134:137], v[174:177], v[50:53]
	v_mfma_f32_16x16x32_bf16 v[34:37], v[134:137], v[214:217], v[34:37]
	v_mfma_f32_16x16x32_bf16 v[30:33], v[142:145], v[214:217], v[30:33]
	v_mfma_f32_16x16x32_bf16 v[14:17], v[142:145], v[222:225], v[14:17]
	v_mfma_f32_16x16x32_bf16 v[18:21], v[134:137], v[222:225], v[18:21]
	v_mfma_f32_16x16x32_bf16 v[66:69], v[138:141], v[170:173], v[66:69]
	v_mfma_f32_16x16x32_bf16 v[62:65], v[146:149], v[170:173], v[62:65]
	v_mfma_f32_16x16x32_bf16 v[46:49], v[146:149], v[178:181], v[46:49]
	v_mfma_f32_16x16x32_bf16 v[50:53], v[138:141], v[178:181], v[50:53]
	v_mfma_f32_16x16x32_bf16 v[34:37], v[138:141], v[218:221], v[34:37]
	v_mfma_f32_16x16x32_bf16 v[30:33], v[146:149], v[218:221], v[30:33]
	v_mfma_f32_16x16x32_bf16 v[14:17], v[146:149], v[226:229], v[14:17]
	v_mfma_f32_16x16x32_bf16 v[18:21], v[138:141], v[226:229], v[18:21]
	s_setprio 0
	s_setprio 1
	v_mfma_f32_16x16x32_bf16 v[58:61], v[150:153], v[166:169], v[58:61]
	v_mfma_f32_16x16x32_bf16 v[54:57], v[158:161], v[166:169], v[54:57]
	v_mfma_f32_16x16x32_bf16 v[38:41], v[158:161], v[174:177], v[38:41]
	v_mfma_f32_16x16x32_bf16 v[42:45], v[150:153], v[174:177], v[42:45]
	v_mfma_f32_16x16x32_bf16 v[26:29], v[150:153], v[214:217], v[26:29]
	v_mfma_f32_16x16x32_bf16 v[22:25], v[158:161], v[214:217], v[22:25]
	v_mfma_f32_16x16x32_bf16 v[6:9], v[158:161], v[222:225], v[6:9]
	v_mfma_f32_16x16x32_bf16 v[10:13], v[150:153], v[222:225], v[10:13]
	v_mfma_f32_16x16x32_bf16 v[58:61], v[154:157], v[170:173], v[58:61]
	v_mfma_f32_16x16x32_bf16 v[54:57], v[162:165], v[170:173], v[54:57]
	v_mfma_f32_16x16x32_bf16 v[38:41], v[162:165], v[178:181], v[38:41]
	v_mfma_f32_16x16x32_bf16 v[42:45], v[154:157], v[178:181], v[42:45]
	v_mfma_f32_16x16x32_bf16 v[26:29], v[154:157], v[218:221], v[26:29]
	v_mfma_f32_16x16x32_bf16 v[22:25], v[162:165], v[218:221], v[22:25]
	v_mfma_f32_16x16x32_bf16 v[6:9], v[162:165], v[226:229], v[6:9]
	v_mfma_f32_16x16x32_bf16 v[10:13], v[154:157], v[226:229], v[10:13]
	s_setprio 0
	s_barrier
	s_add_i32 s56, s56, 2
	s_add_u32 s26, s26, 0x100
	s_addc_u32 s27, s27, 0
	s_add_u32 s34, s34, 0x100
	s_addc_u32 s55, s55, 0
	s_cmp_gt_u32 s56, 29
	s_cbranch_scc0 .LBB0_655
	s_and_b64 vcc, exec, s[12:13]
	s_cbranch_vccz .LBB0_658
	s_barrier

; #define PG8_STAGE(bufoff, gbase, voff) do { _Pragma("unroll") for (int _i = 0; _i < 2; ++_i) \
;         __builtin_amdgcn_global_load_lds((const unsigned*)((const char*)(gbase) + (voff)[_i]), (LAS unsigned*)(lds + (bufoff) + ldsw + _i * 8192), 16, 0, 0); } while (0)
; #define PG8_LDA(dst, b, h) do { _Pragma("unroll") for (int m = 0; m < 4; ++m) _Pragma("unroll") for (int k = 0; k < 2; ++k) dst[m][k] = *(const LAS bf16x8*)(lds + PG8_SA(b, h) + aoff + m * 2048 + k * 1024); } while (0)
; #define PG8_LDB(dst, b, h) do { _Pragma("unroll") for (int n = 0; n < 2; ++n) _Pragma("unroll") for (int k = 0; k < 2; ++k) dst[n][k] = *(const LAS bf16x8*)(lds + PG8_SB(b, h) + boff + n * 2048 + k * 1024); } while (0)
; #define PG8_MMA(ai, bj, At, Bt) do { __builtin_amdgcn_s_setprio(1); _Pragma("unroll") for (int m = 0; m < 4; ++m) _Pragma("unroll") for (int n = 0; n < 2; ++n) _Pragma("unroll") for (int k = 0; k < 2; ++k) \
;         acc[ai][bj][m][n] = __builtin_amdgcn_mfma_f32_16x16x32_bf16(Bt[n][k], At[m][k], acc[ai][bj][m][n], 0, 0, 0); __builtin_amdgcn_s_setprio(0); } while (0)
; #define PG8_WAIT_V(n) asm volatile("s_waitcnt vmcnt(" #n ")" ::: "memory")
; #define PG8_WAIT_L(n) asm volatile("s_waitcnt lgkmcnt(" #n ")" ::: "memory")
; #define PG8_BAR __builtin_amdgcn_s_barrier()
; #define PG8_SCHED __builtin_amdgcn_sched_barrier(0)
; template <class Epi, class Sched>
; __device__ __forceinline__ void gemm_phase(LAS unsigned char* lds, const Gemm g, const Sched& S, const Epi& E) {
;     ...
;             PG8_LDB(B0, 0, 0); PG8_LDB(B1, 0, 1); PG8_SCHED; PG8_LDA(At, 0, 0); PG8_STAGE(PG8_SA(1, 1), a1 + hstepA, voffA);
;             PG8_WAIT_V(8); PG8_WAIT_L(0); PG8_BAR; PG8_MMA(0, 0, At, B0); PG8_MMA(0, 1, At, B1); PG8_BAR; PG8_SCHED;
;             PG8_LDA(At, 0, 1); PG8_STAGE(PG8_SB(0, 0), b2, voffB); PG8_STAGE(PG8_SB(0, 1), b2 + hstepB, voffB); PG8_STAGE(PG8_SA(0, 0), a2, voffA);
.LBB0_1009:
	s_add_i32 s43, s48, 2
	s_add_u32 s70, s26, s46
	s_addc_u32 s49, s27, s47
	s_add_u32 s72, s24, s46
	s_addc_u32 s71, s25, s47
	s_add_i32 s73, 0, 0x10000
	s_cmp_eq_u32 s65, s48
	s_cselect_b32 s49, s5, s49
	s_cselect_b32 s48, s4, s70
	v_add_u32_e32 v4, s73, v148
	s_cselect_b32 s71, s45, s71
	s_cselect_b32 s70, s44, s72
	s_add_i32 s72, 0, 0x14000
	ds_read_b128 v[150:153], v4
	ds_read_b128 v[154:157], v4 offset:1024
	ds_read_b128 v[158:161], v4 offset:2048
	ds_read_b128 v[162:165], v4 offset:3072
	v_add_u32_e32 v4, s72, v148
	ds_read_b128 v[170:173], v4
	ds_read_b128 v[174:177], v4 offset:1024
	ds_read_b128 v[178:181], v4 offset:2048
	ds_read_b128 v[182:185], v4 offset:3072
	v_lshl_add_u64 v[166:167], s[26:27], 0, v[146:147]
	s_add_i32 m0, s58, 0xc000
	ds_read_b128 v[186:189], v149
	ds_read_b128 v[190:193], v149 offset:1024
	ds_read_b128 v[194:197], v149 offset:2048
	ds_read_b128 v[212:215], v149 offset:3072
	ds_read_b128 v[216:219], v149 offset:4096
	ds_read_b128 v[220:223], v149 offset:5120
	ds_read_b128 v[224:227], v149 offset:6144
	ds_read_b128 v[228:231], v149 offset:7168
	global_load_lds_dwordx4 v[166:167], off
	v_lshl_add_u64 v[166:167], s[26:27], 0, v[2:3]
	s_add_i32 m0, s58, 0xe000
	s_nop 0
	global_load_lds_dwordx4 v[166:167], off
	s_waitcnt vmcnt(8)
	s_waitcnt lgkmcnt(0)
	s_barrier
	s_setprio 1
	s_waitcnt lgkmcnt(0)
	v_mfma_f32_16x16x32_bf16 v[130:133], v[150:153], v[186:189], v[130:133]
	v_mfma_f32_16x16x32_bf16 v[126:129], v[158:161], v[186:189], v[126:129]
	v_mfma_f32_16x16x32_bf16 v[118:121], v[158:161], v[194:197], v[118:121]
	v_mfma_f32_16x16x32_bf16 v[122:125], v[150:153], v[194:197], v[122:125]
	v_mfma_f32_16x16x32_bf16 v[110:113], v[150:153], v[216:219], v[110:113]
	v_mfma_f32_16x16x32_bf16 v[106:109], v[158:161], v[216:219], v[106:109]
	v_mfma_f32_16x16x32_bf16 v[90:93], v[158:161], v[224:227], v[90:93]
	v_mfma_f32_16x16x32_bf16 v[98:101], v[150:153], v[224:227], v[98:101]
	v_mfma_f32_16x16x32_bf16 v[130:133], v[154:157], v[190:193], v[130:133]
	v_mfma_f32_16x16x32_bf16 v[126:129], v[162:165], v[190:193], v[126:129]
	v_mfma_f32_16x16x32_bf16 v[118:121], v[162:165], v[212:215], v[118:121]
	v_mfma_f32_16x16x32_bf16 v[122:125], v[154:157], v[212:215], v[122:125]
	v_mfma_f32_16x16x32_bf16 v[110:113], v[154:157], v[220:223], v[110:113]
	v_mfma_f32_16x16x32_bf16 v[106:109], v[162:165], v[220:223], v[106:109]
	v_mfma_f32_16x16x32_bf16 v[90:93], v[162:165], v[228:231], v[90:93]
	v_mfma_f32_16x16x32_bf16 v[98:101], v[154:157], v[228:231], v[98:101]
	s_setprio 0
	s_setprio 1
	v_mfma_f32_16x16x32_bf16 v[114:117], v[170:173], v[186:189], v[114:117]
	v_mfma_f32_16x16x32_bf16 v[102:105], v[178:181], v[186:189], v[102:105]
	v_mfma_f32_16x16x32_bf16 v[86:89], v[178:181], v[194:197], v[86:89]
	v_mfma_f32_16x16x32_bf16 v[94:97], v[170:173], v[194:197], v[94:97]
	v_mfma_f32_16x16x32_bf16 v[82:85], v[170:173], v[216:219], v[82:85]
	v_mfma_f32_16x16x32_bf16 v[78:81], v[178:181], v[216:219], v[78:81]
	v_mfma_f32_16x16x32_bf16 v[70:73], v[178:181], v[224:227], v[70:73]
	v_mfma_f32_16x16x32_bf16 v[74:77], v[170:173], v[224:227], v[74:77]
	v_mfma_f32_16x16x32_bf16 v[114:117], v[174:177], v[190:193], v[114:117]
	v_mfma_f32_16x16x32_bf16 v[102:105], v[182:185], v[190:193], v[102:105]
	v_mfma_f32_16x16x32_bf16 v[86:89], v[182:185], v[212:215], v[86:89]
	v_mfma_f32_16x16x32_bf16 v[94:97], v[174:177], v[212:215], v[94:97]
	v_mfma_f32_16x16x32_bf16 v[82:85], v[174:177], v[220:223], v[82:85]
	v_mfma_f32_16x16x32_bf16 v[78:81], v[182:185], v[220:223], v[78:81]
	v_mfma_f32_16x16x32_bf16 v[70:73], v[182:185], v[228:231], v[70:73]
	v_mfma_f32_16x16x32_bf16 v[74:77], v[174:177], v[228:231], v[74:77]
	s_setprio 0
	s_barrier
	s_add_i32 s73, s73, s57
	v_lshl_add_u64 v[166:167], s[70:71], 0, v[138:139]
	s_mov_b32 m0, s73
	ds_read_b128 v[186:189], v149 offset:16384
	ds_read_b128 v[190:193], v149 offset:17408
	ds_read_b128 v[194:197], v149 offset:18432
	ds_read_b128 v[212:215], v149 offset:19456
	ds_read_b128 v[216:219], v149 offset:20480
	ds_read_b128 v[220:223], v149 offset:21504
	ds_read_b128 v[224:227], v149 offset:22528
	ds_read_b128 v[228:231], v149 offset:23552
	global_load_lds_dwordx4 v[166:167], off
	s_add_i32 m0, s73, 0x2000
	v_lshl_add_u64 v[236:237], s[70:71], 0, v[134:135]
	s_add_u32 s70, s70, s55
	s_addc_u32 s71, s71, 0
	s_add_i32 s72, s72, s57
	global_load_lds_dwordx4 v[236:237], off
	v_lshl_add_u64 v[238:239], s[70:71], 0, v[138:139]
	s_mov_b32 m0, s72
	v_lshl_add_u64 v[240:241], s[70:71], 0, v[134:135]
	global_load_lds_dwordx4 v[238:239], off
	s_add_i32 m0, s72, 0x2000
	v_lshl_add_u64 v[242:243], s[48:49], 0, v[140:141]
	global_load_lds_dwordx4 v[240:241], off
	s_mov_b32 m0, s58
	v_lshl_add_u64 v[244:245], s[48:49], 0, v[136:137]
	global_load_lds_dwordx4 v[242:243], off
	s_mov_b32 m0, s59
	s_nop 0
	global_load_lds_dwordx4 v[244:245], off
	s_waitcnt vmcnt(8)
	s_waitcnt lgkmcnt(0)
	s_barrier
; #define PG8_STAGE(bufoff, gbase, voff) do { _Pragma("unroll") for (int _i = 0; _i < 2; ++_i) \
;         __builtin_amdgcn_global_load_lds((const unsigned*)((const char*)(gbase) + (voff)[_i]), (LAS unsigned*)(lds + (bufoff) + ldsw + _i * 8192), 16, 0, 0); } while (0)
; #define PG8_LDA(dst, b, h) do { _Pragma("unroll") for (int m = 0; m < 4; ++m) _Pragma("unroll") for (int k = 0; k < 2; ++k) dst[m][k] = *(const LAS bf16x8*)(lds + PG8_SA(b, h) + aoff + m * 2048 + k * 1024); } while (0)
; #define PG8_LDB(dst, b, h) do { _Pragma("unroll") for (int n = 0; n < 2; ++n) _Pragma("unroll") for (int k = 0; k < 2; ++k) dst[n][k] = *(const LAS bf16x8*)(lds + PG8_SB(b, h) + boff + n * 2048 + k * 1024); } while (0)
; #define PG8_MMA(ai, bj, At, Bt) do { __builtin_amdgcn_s_setprio(1); _Pragma("unroll") for (int m = 0; m < 4; ++m) _Pragma("unroll") for (int n = 0; n < 2; ++n) _Pragma("unroll") for (int k = 0; k < 2; ++k) \
;         acc[ai][bj][m][n] = __builtin_amdgcn_mfma_f32_16x16x32_bf16(Bt[n][k], At[m][k], acc[ai][bj][m][n], 0, 0, 0); __builtin_amdgcn_s_setprio(0); } while (0)
; #define PG8_WAIT_V(n) asm volatile("s_waitcnt vmcnt(" #n ")" ::: "memory")
; #define PG8_WAIT_L(n) asm volatile("s_waitcnt lgkmcnt(" #n ")" ::: "memory")
; #define PG8_BAR __builtin_amdgcn_s_barrier()
; #define PG8_SCHED __builtin_amdgcn_sched_barrier(0)
; template <class Epi, class Sched>
; __device__ __forceinline__ void gemm_phase(LAS unsigned char* lds, const Gemm g, const Sched& S, const Epi& E) {
;     ...
;             PG8_WAIT_V(8); PG8_WAIT_L(0); PG8_BAR; PG8_MMA(1, 0, At, B0); PG8_MMA(1, 1, At, B1); PG8_BAR; PG8_SCHED;
;             PG8_LDB(B0, 1, 0); PG8_LDB(B1, 1, 1); PG8_SCHED; PG8_LDA(At, 1, 0); PG8_STAGE(PG8_SA(0, 1), a2 + hstepA, voffA);
;             PG8_WAIT_V(8); PG8_WAIT_L(0); PG8_BAR; PG8_MMA(0, 0, At, B0); PG8_MMA(0, 1, At, B1); PG8_BAR; PG8_SCHED;
	s_setprio 1
	s_waitcnt lgkmcnt(0)
	v_mfma_f32_16x16x32_bf16 v[66:69], v[150:153], v[186:189], v[66:69]
	v_mfma_f32_16x16x32_bf16 v[62:65], v[158:161], v[186:189], v[62:65]
	v_mfma_f32_16x16x32_bf16 v[54:57], v[158:161], v[194:197], v[54:57]
	v_mfma_f32_16x16x32_bf16 v[58:61], v[150:153], v[194:197], v[58:61]
	v_mfma_f32_16x16x32_bf16 v[50:53], v[150:153], v[216:219], v[50:53]
	v_mfma_f32_16x16x32_bf16 v[42:45], v[158:161], v[216:219], v[42:45]
	v_mfma_f32_16x16x32_bf16 v[26:29], v[158:161], v[224:227], v[26:29]
	v_mfma_f32_16x16x32_bf16 v[34:37], v[150:153], v[224:227], v[34:37]
	v_mfma_f32_16x16x32_bf16 v[66:69], v[154:157], v[190:193], v[66:69]
	v_mfma_f32_16x16x32_bf16 v[62:65], v[162:165], v[190:193], v[62:65]
	v_mfma_f32_16x16x32_bf16 v[54:57], v[162:165], v[212:215], v[54:57]
	v_mfma_f32_16x16x32_bf16 v[58:61], v[154:157], v[212:215], v[58:61]
	v_mfma_f32_16x16x32_bf16 v[50:53], v[154:157], v[220:223], v[50:53]
	v_mfma_f32_16x16x32_bf16 v[42:45], v[162:165], v[220:223], v[42:45]
	v_mfma_f32_16x16x32_bf16 v[26:29], v[162:165], v[228:231], v[26:29]
	v_mfma_f32_16x16x32_bf16 v[34:37], v[154:157], v[228:231], v[34:37]
	s_setprio 0
	s_setprio 1
	v_mfma_f32_16x16x32_bf16 v[46:49], v[170:173], v[186:189], v[46:49]
	v_mfma_f32_16x16x32_bf16 v[38:41], v[178:181], v[186:189], v[38:41]
	v_mfma_f32_16x16x32_bf16 v[22:25], v[178:181], v[194:197], v[22:25]
	v_mfma_f32_16x16x32_bf16 v[30:33], v[170:173], v[194:197], v[30:33]
	v_mfma_f32_16x16x32_bf16 v[18:21], v[170:173], v[216:219], v[18:21]
	v_mfma_f32_16x16x32_bf16 v[14:17], v[178:181], v[216:219], v[14:17]
	v_mfma_f32_16x16x32_bf16 v[6:9], v[178:181], v[224:227], v[6:9]
	v_mfma_f32_16x16x32_bf16 v[10:13], v[170:173], v[224:227], v[10:13]
	v_mfma_f32_16x16x32_bf16 v[46:49], v[174:177], v[190:193], v[46:49]
	v_mfma_f32_16x16x32_bf16 v[38:41], v[182:185], v[190:193], v[38:41]
	v_mfma_f32_16x16x32_bf16 v[22:25], v[182:185], v[212:215], v[22:25]
	v_mfma_f32_16x16x32_bf16 v[30:33], v[174:177], v[212:215], v[30:33]
	v_mfma_f32_16x16x32_bf16 v[18:21], v[174:177], v[220:223], v[18:21]
	v_mfma_f32_16x16x32_bf16 v[14:17], v[182:185], v[220:223], v[14:17]
	v_mfma_f32_16x16x32_bf16 v[6:9], v[182:185], v[228:231], v[6:9]
	v_mfma_f32_16x16x32_bf16 v[10:13], v[174:177], v[228:231], v[10:13]
	s_setprio 0
	s_barrier
	s_add_i32 s70, 0, 0x18000
	v_add_u32_e32 v4, s70, v148
	s_add_i32 s71, 0, 0x1c000
	ds_read_b128 v[150:153], v4
	ds_read_b128 v[154:157], v4 offset:1024
	ds_read_b128 v[158:161], v4 offset:2048
	ds_read_b128 v[162:165], v4 offset:3072
	v_add_u32_e32 v4, s71, v148
	ds_read_b128 v[170:173], v4
	ds_read_b128 v[174:177], v4 offset:1024
	ds_read_b128 v[178:181], v4 offset:2048
	ds_read_b128 v[182:185], v4 offset:3072
	s_add_u32 s48, s48, s34
	s_addc_u32 s49, s49, 0
	s_mov_b32 m0, s60
	v_lshl_add_u64 v[246:247], s[48:49], 0, v[140:141]
	ds_read_b128 v[186:189], v149 offset:32768
	ds_read_b128 v[190:193], v149 offset:33792
	ds_read_b128 v[194:197], v149 offset:34816
	ds_read_b128 v[212:215], v149 offset:35840
	ds_read_b128 v[216:219], v149 offset:36864
	ds_read_b128 v[220:223], v149 offset:37888
	ds_read_b128 v[224:227], v149 offset:38912
	ds_read_b128 v[228:231], v149 offset:39936
	global_load_lds_dwordx4 v[246:247], off
	v_lshl_add_u64 v[246:247], s[48:49], 0, v[136:137]
	s_mov_b32 m0, s61
	s_nop 0
	global_load_lds_dwordx4 v[246:247], off
	s_waitcnt vmcnt(8)
	s_waitcnt lgkmcnt(0)
	s_barrier
	s_setprio 1
	s_waitcnt lgkmcnt(0)
	v_mfma_f32_16x16x32_bf16 v[130:133], v[150:153], v[186:189], v[130:133]
	v_mfma_f32_16x16x32_bf16 v[126:129], v[158:161], v[186:189], v[126:129]
	v_mfma_f32_16x16x32_bf16 v[118:121], v[158:161], v[194:197], v[118:121]
	v_mfma_f32_16x16x32_bf16 v[122:125], v[150:153], v[194:197], v[122:125]
	v_mfma_f32_16x16x32_bf16 v[110:113], v[150:153], v[216:219], v[110:113]
	v_mfma_f32_16x16x32_bf16 v[106:109], v[158:161], v[216:219], v[106:109]
	v_mfma_f32_16x16x32_bf16 v[90:93], v[158:161], v[224:227], v[90:93]
	v_mfma_f32_16x16x32_bf16 v[98:101], v[150:153], v[224:227], v[98:101]
	v_mfma_f32_16x16x32_bf16 v[130:133], v[154:157], v[190:193], v[130:133]
	v_mfma_f32_16x16x32_bf16 v[126:129], v[162:165], v[190:193], v[126:129]
	v_mfma_f32_16x16x32_bf16 v[118:121], v[162:165], v[212:215], v[118:121]
	v_mfma_f32_16x16x32_bf16 v[122:125], v[154:157], v[212:215], v[122:125]
	v_mfma_f32_16x16x32_bf16 v[110:113], v[154:157], v[220:223], v[110:113]
	v_mfma_f32_16x16x32_bf16 v[106:109], v[162:165], v[220:223], v[106:109]
	v_mfma_f32_16x16x32_bf16 v[90:93], v[162:165], v[228:231], v[90:93]
	v_mfma_f32_16x16x32_bf16 v[98:101], v[154:157], v[228:231], v[98:101]
	s_setprio 0
	s_setprio 1
	v_mfma_f32_16x16x32_bf16 v[114:117], v[170:173], v[186:189], v[114:117]
	v_mfma_f32_16x16x32_bf16 v[102:105], v[178:181], v[186:189], v[102:105]
	v_mfma_f32_16x16x32_bf16 v[86:89], v[178:181], v[194:197], v[86:89]
	v_mfma_f32_16x16x32_bf16 v[94:97], v[170:173], v[194:197], v[94:97]
	v_mfma_f32_16x16x32_bf16 v[82:85], v[170:173], v[216:219], v[82:85]
	v_mfma_f32_16x16x32_bf16 v[78:81], v[178:181], v[216:219], v[78:81]
	v_mfma_f32_16x16x32_bf16 v[70:73], v[178:181], v[224:227], v[70:73]
	v_mfma_f32_16x16x32_bf16 v[74:77], v[170:173], v[224:227], v[74:77]
	v_mfma_f32_16x16x32_bf16 v[114:117], v[174:177], v[190:193], v[114:117]
	v_mfma_f32_16x16x32_bf16 v[102:105], v[182:185], v[190:193], v[102:105]
	v_mfma_f32_16x16x32_bf16 v[86:89], v[182:185], v[212:215], v[86:89]
	v_mfma_f32_16x16x32_bf16 v[94:97], v[174:177], v[212:215], v[94:97]
	v_mfma_f32_16x16x32_bf16 v[82:85], v[174:177], v[220:223], v[82:85]
	v_mfma_f32_16x16x32_bf16 v[78:81], v[182:185], v[220:223], v[78:81]
	v_mfma_f32_16x16x32_bf16 v[70:73], v[182:185], v[228:231], v[70:73]
	v_mfma_f32_16x16x32_bf16 v[74:77], v[174:177], v[228:231], v[74:77]
	s_setprio 0
	s_barrier
; #define PG8_STAGE(bufoff, gbase, voff) do { _Pragma("unroll") for (int _i = 0; _i < 2; ++_i) \
;         __builtin_amdgcn_global_load_lds((const unsigned*)((const char*)(gbase) + (voff)[_i]), (LAS unsigned*)(lds + (bufoff) + ldsw + _i * 8192), 16, 0, 0); } while (0)
; #define PG8_LDA(dst, b, h) do { _Pragma("unroll") for (int m = 0; m < 4; ++m) _Pragma("unroll") for (int k = 0; k < 2; ++k) dst[m][k] = *(const LAS bf16x8*)(lds + PG8_SA(b, h) + aoff + m * 2048 + k * 1024); } while (0)
; #define PG8_MMA(ai, bj, At, Bt) do { __builtin_amdgcn_s_setprio(1); _Pragma("unroll") for (int m = 0; m < 4; ++m) _Pragma("unroll") for (int n = 0; n < 2; ++n) _Pragma("unroll") for (int k = 0; k < 2; ++k) \
;         acc[ai][bj][m][n] = __builtin_amdgcn_mfma_f32_16x16x32_bf16(Bt[n][k], At[m][k], acc[ai][bj][m][n], 0, 0, 0); __builtin_amdgcn_s_setprio(0); } while (0)
; #define PG8_WAIT_V(n) asm volatile("s_waitcnt vmcnt(" #n ")" ::: "memory")
; #define PG8_WAIT_L(n) asm volatile("s_waitcnt lgkmcnt(" #n ")" ::: "memory")
; #define PG8_BAR __builtin_amdgcn_s_barrier()
; #define PG8_SCHED __builtin_amdgcn_sched_barrier(0)
; template <class Epi, class Sched>
; __device__ __forceinline__ void gemm_phase(LAS unsigned char* lds, const Gemm g, const Sched& S, const Epi& E) {
;     ...
;         for (int t = 0; t < nt; t += 2) {
;     ...
;             PG8_LDA(At, 1, 1); PG8_STAGE(PG8_SB(1, 0), b3, voffB); PG8_STAGE(PG8_SB(1, 1), b3 + hstepB, voffB); PG8_STAGE(PG8_SA(1, 0), a3, voffA);
;             PG8_WAIT_V(8); PG8_WAIT_L(0); PG8_BAR; PG8_MMA(1, 0, At, B0); PG8_MMA(1, 1, At, B1); PG8_BAR; PG8_SCHED;
;         }
	s_add_i32 s48, s70, s57
	v_lshl_add_u64 v[166:167], v[166:167], 0, s[36:37]
	s_mov_b32 m0, s48
	ds_read_b128 v[186:189], v149 offset:49152
	ds_read_b128 v[190:193], v149 offset:50176
	ds_read_b128 v[194:197], v149 offset:51200
	ds_read_b128 v[212:215], v149 offset:52224
	ds_read_b128 v[216:219], v149 offset:53248
	ds_read_b128 v[220:223], v149 offset:54272
	ds_read_b128 v[224:227], v149 offset:55296
	ds_read_b128 v[228:231], v149 offset:56320
	global_load_lds_dwordx4 v[166:167], off
	v_lshl_add_u64 v[166:167], v[236:237], 0, s[36:37]
	s_add_i32 m0, s48, 0x2000
	s_add_i32 s48, s71, s57
	global_load_lds_dwordx4 v[166:167], off
	v_lshl_add_u64 v[166:167], v[238:239], 0, s[36:37]
	s_mov_b32 m0, s48
	s_nop 0
	global_load_lds_dwordx4 v[166:167], off
	v_lshl_add_u64 v[166:167], v[240:241], 0, s[36:37]
	s_add_i32 m0, s48, 0x2000
	s_nop 0
	global_load_lds_dwordx4 v[166:167], off
	v_lshl_add_u64 v[166:167], v[242:243], 0, s[36:37]
	s_mov_b32 m0, s62
	s_nop 0
	global_load_lds_dwordx4 v[166:167], off
	v_lshl_add_u64 v[166:167], v[244:245], 0, s[36:37]
	s_mov_b32 m0, s63
	s_nop 0
	global_load_lds_dwordx4 v[166:167], off
	s_waitcnt vmcnt(8)
	s_waitcnt lgkmcnt(0)
	s_barrier
	s_setprio 1
	s_waitcnt lgkmcnt(0)
	v_mfma_f32_16x16x32_bf16 v[66:69], v[150:153], v[186:189], v[66:69]
	v_mfma_f32_16x16x32_bf16 v[62:65], v[158:161], v[186:189], v[62:65]
	v_mfma_f32_16x16x32_bf16 v[54:57], v[158:161], v[194:197], v[54:57]
	v_mfma_f32_16x16x32_bf16 v[58:61], v[150:153], v[194:197], v[58:61]
	v_mfma_f32_16x16x32_bf16 v[50:53], v[150:153], v[216:219], v[50:53]
	v_mfma_f32_16x16x32_bf16 v[42:45], v[158:161], v[216:219], v[42:45]
	v_mfma_f32_16x16x32_bf16 v[26:29], v[158:161], v[224:227], v[26:29]
	v_mfma_f32_16x16x32_bf16 v[34:37], v[150:153], v[224:227], v[34:37]
	v_mfma_f32_16x16x32_bf16 v[66:69], v[154:157], v[190:193], v[66:69]
	v_mfma_f32_16x16x32_bf16 v[62:65], v[162:165], v[190:193], v[62:65]
	v_mfma_f32_16x16x32_bf16 v[54:57], v[162:165], v[212:215], v[54:57]
	v_mfma_f32_16x16x32_bf16 v[58:61], v[154:157], v[212:215], v[58:61]
	v_mfma_f32_16x16x32_bf16 v[50:53], v[154:157], v[220:223], v[50:53]
	v_mfma_f32_16x16x32_bf16 v[42:45], v[162:165], v[220:223], v[42:45]
	v_mfma_f32_16x16x32_bf16 v[26:29], v[162:165], v[228:231], v[26:29]
	v_mfma_f32_16x16x32_bf16 v[34:37], v[154:157], v[228:231], v[34:37]
	s_setprio 0
	s_setprio 1
	v_mfma_f32_16x16x32_bf16 v[46:49], v[170:173], v[186:189], v[46:49]
	v_mfma_f32_16x16x32_bf16 v[38:41], v[178:181], v[186:189], v[38:41]
	v_mfma_f32_16x16x32_bf16 v[22:25], v[178:181], v[194:197], v[22:25]
	v_mfma_f32_16x16x32_bf16 v[30:33], v[170:173], v[194:197], v[30:33]
	v_mfma_f32_16x16x32_bf16 v[18:21], v[170:173], v[216:219], v[18:21]
	v_mfma_f32_16x16x32_bf16 v[14:17], v[178:181], v[216:219], v[14:17]
	v_mfma_f32_16x16x32_bf16 v[6:9], v[178:181], v[224:227], v[6:9]
	v_mfma_f32_16x16x32_bf16 v[10:13], v[170:173], v[224:227], v[10:13]
	v_mfma_f32_16x16x32_bf16 v[46:49], v[174:177], v[190:193], v[46:49]
	v_mfma_f32_16x16x32_bf16 v[38:41], v[182:185], v[190:193], v[38:41]
	v_mfma_f32_16x16x32_bf16 v[22:25], v[182:185], v[212:215], v[22:25]
	v_mfma_f32_16x16x32_bf16 v[30:33], v[174:177], v[212:215], v[30:33]
	v_mfma_f32_16x16x32_bf16 v[18:21], v[174:177], v[220:223], v[18:21]
	v_mfma_f32_16x16x32_bf16 v[14:17], v[182:185], v[220:223], v[14:17]
	v_mfma_f32_16x16x32_bf16 v[6:9], v[182:185], v[228:231], v[6:9]
	v_mfma_f32_16x16x32_bf16 v[10:13], v[174:177], v[228:231], v[10:13]
	s_setprio 0
	s_barrier
	s_add_u32 s46, s46, 0x100
	s_addc_u32 s47, s47, 0
	v_lshl_add_u64 v[146:147], v[146:147], 0, s[30:31]
	v_lshl_add_u64 v[2:3], v[2:3], 0, s[30:31]
	s_cmp_ge_u32 s43, s64
	s_mov_b32 s48, s43
	s_cbranch_scc0 .LBB0_1009
	s_and_b64 vcc, exec, s[28:29]
	s_cbranch_vccz .LBB0_1012
	s_barrier
